# conv LayerNorm stage: conv_ln_g/b staged once per workgroup in 8 KiB static LDS and read by ds_read_b128 in the token loop (removes 64 global-load round trips per workgroup); ProbGlu epilogue batched
# speedup vs baseline: 1.0473x; 1.0158x over previous
.LBB0_400:
	v_readlane_b32 s2, v240, 17
	s_ashr_i32 s2, s2, 7
	s_lshl_b32 s12, s12, 4
	s_add_i32 s2, s2, s3
	s_lshl_b32 s10, s2, 6
	s_and_b32 s2, s12, 16
	s_ashr_i32 s33, s10, 31
	s_or_b32 s4, s2, s0
	s_add_u32 s11, s14, s10
	s_addc_u32 s5, s15, s33
	s_or_b32 s4, s11, s4
	s_lshl_b64 s[30:31], s[4:5], 12
	v_readlane_b32 s48, v241, 0
	v_readlane_b32 s49, v241, 1
	s_add_u32 s34, s48, s30
	s_addc_u32 s35, s49, s31
	s_lshl_b64 s[30:31], s[4:5], 11
	s_add_u32 s30, s38, s30
	s_addc_u32 s31, s39, s31
	v_readlane_b32 s4, v240, 15
	s_add_u32 s4, s4, s10
	s_addc_u32 s37, s13, s33
	s_or_b32 s4, s2, s4
	v_lshlrev_b32_e32 v12, 3, v168
	s_or_b32 s36, s4, 1
	v_readlane_b32 s20, v241, 22
	v_readlane_b32 s21, v241, 23
	v_readlane_b32 s22, v241, 24
	v_readlane_b32 s23, v241, 25
	v_readfirstlane_b32 s98, v193
	v_lshlrev_b32_e32 v248, 4, v193
	v_and_b32_e32 v249, 63, v193
	s_cmp_lt_u32 s98, 0x100
	s_cselect_b32 s20, s20, s22
	s_cselect_b32 s21, s21, s23
	v_and_b32_e32 v246, 0xfff, v248
	v_lshlrev_b32_e32 v249, 4, v249
	global_load_dwordx4 v[242:245], v246, s[20:21]
	v_add_u32_e32 v248, 0x20100, v248
	v_add_u32_e32 v249, 0x20100, v249
	s_waitcnt vmcnt(0)
	ds_write_b128 v248, v[242:245]
	s_waitcnt lgkmcnt(0)
	s_barrier
	global_load_dwordx2 v[4:5], v12, s[34:35]
	global_load_dwordx2 v[6:7], v12, s[34:35] offset:512
	global_load_dwordx2 v[8:9], v12, s[34:35] offset:1024
	global_load_dwordx2 v[10:11], v12, s[34:35] offset:1536
	s_lshl_b64 s[34:35], s[36:37], 12
	s_add_u32 s34, s48, s34
	s_addc_u32 s35, s49, s35
	s_lshl_b64 s[44:45], s[36:37], 11
	s_add_u32 s44, s38, s44
	s_addc_u32 s45, s39, s45
	s_or_b32 s36, s4, 2
	global_load_dwordx2 v[16:17], v12, s[34:35]
	global_load_dwordx2 v[20:21], v12, s[34:35] offset:512
	global_load_dwordx2 v[22:23], v12, s[34:35] offset:1024
	global_load_dwordx2 v[24:25], v12, s[34:35] offset:1536
	s_lshl_b64 s[34:35], s[36:37], 12
	s_add_u32 s34, s48, s34
	s_addc_u32 s35, s49, s35
	s_lshl_b64 s[46:47], s[36:37], 11
	s_add_u32 s46, s38, s46
	s_addc_u32 s47, s39, s47
	s_or_b32 s36, s4, 3
	global_load_dwordx2 v[26:27], v12, s[34:35]
	global_load_dwordx2 v[28:29], v12, s[34:35] offset:512
	global_load_dwordx2 v[30:31], v12, s[34:35] offset:1024
	global_load_dwordx2 v[32:33], v12, s[34:35] offset:1536
	s_lshl_b64 s[34:35], s[36:37], 12
	s_add_u32 s34, s48, s34
	s_addc_u32 s35, s49, s35
	global_load_dwordx2 v[34:35], v12, s[34:35]
	global_load_dwordx2 v[36:37], v12, s[34:35] offset:512
	global_load_dwordx2 v[44:45], v12, s[34:35] offset:1024
	global_load_dwordx2 v[174:175], v12, s[30:31]
	global_load_dwordx2 v[170:171], v12, s[30:31] offset:512
	global_load_dwordx2 v[166:167], v12, s[30:31] offset:1024
	global_load_dwordx2 v[160:161], v12, s[30:31] offset:1536
	global_load_dwordx2 v[46:47], v12, s[34:35] offset:1536
	global_load_dwordx2 v[154:155], v12, s[44:45]
	global_load_dwordx2 v[146:147], v12, s[44:45] offset:512
	global_load_dwordx2 v[142:143], v12, s[44:45] offset:1024
	global_load_dwordx2 v[136:137], v12, s[44:45] offset:1536
	global_load_dwordx2 v[130:131], v12, s[46:47]
	global_load_dwordx2 v[122:123], v12, s[46:47] offset:512
	global_load_dwordx2 v[118:119], v12, s[46:47] offset:1024
	global_load_dwordx2 v[108:109], v12, s[46:47] offset:1536
	s_lshl_b64 s[30:31], s[36:37], 11
	s_add_u32 s30, s38, s30
	s_addc_u32 s31, s39, s31
	global_load_dwordx2 v[42:43], v12, s[30:31]
	global_load_dwordx2 v[18:19], v12, s[30:31] offset:512
	global_load_dwordx2 v[14:15], v12, s[30:31] offset:1024
	global_load_dwordx2 v[2:3], v12, s[30:31] offset:1536
	v_readlane_b32 s16, v241, 18
	v_readlane_b32 s17, v241, 19
	v_readlane_b32 s18, v241, 20
	v_readlane_b32 s19, v241, 21
	v_readlane_b32 s20, v241, 22
	v_readlane_b32 s21, v241, 23
	v_mov_b32_e32 v13, 0
	v_readlane_b32 s22, v241, 24
	v_readlane_b32 s23, v241, 25
	s_mov_b64 s[16:17], s[20:21]
	v_mov_b32_e32 v1, v13
	s_mov_b64 s[18:19], s[22:23]
	s_or_b32 s10, s12, 4
	s_mov_b32 s12, 0
	s_mov_b32 s4, 0x3a800000
	s_mov_b32 s13, 0x800000
	v_readlane_b32 s50, v241, 2
	v_readlane_b32 s51, v241, 3
	v_readlane_b32 s52, v241, 4
	v_readlane_b32 s53, v241, 5
	v_readlane_b32 s54, v241, 6
	v_readlane_b32 s55, v241, 7
	v_readlane_b32 s56, v241, 8
	v_readlane_b32 s57, v241, 9
	v_readlane_b32 s58, v241, 10
	v_readlane_b32 s59, v241, 11
	v_readlane_b32 s60, v241, 12
	v_readlane_b32 s61, v241, 13
	v_readlane_b32 s62, v241, 14
	v_readlane_b32 s63, v241, 15
	v_readlane_b32 s24, v241, 26
	v_readlane_b32 s25, v241, 27
	v_readlane_b32 s26, v241, 28
	v_readlane_b32 s27, v241, 29
	v_readlane_b32 s28, v241, 30
	v_readlane_b32 s29, v241, 31
	v_readlane_b32 s30, v241, 32
	v_readlane_b32 s31, v241, 33
	s_waitcnt vmcnt(31)
	v_lshlrev_b32_e32 v183, 16, v5
	v_lshlrev_b32_e32 v182, 16, v4
	v_and_b32_e32 v181, 0xffff0000, v5
	v_and_b32_e32 v180, 0xffff0000, v4
	s_waitcnt vmcnt(30)
	v_lshlrev_b32_e32 v179, 16, v7
	v_lshlrev_b32_e32 v178, 16, v6
	v_and_b32_e32 v177, 0xffff0000, v7
	v_and_b32_e32 v176, 0xffff0000, v6
	s_waitcnt vmcnt(29)
	v_lshlrev_b32_e32 v173, 16, v8
	v_and_b32_e32 v172, 0xffff0000, v8
	v_lshlrev_b32_e32 v141, 16, v9
	v_and_b32_e32 v139, 0xffff0000, v9
	s_waitcnt vmcnt(28)
	v_and_b32_e32 v164, 0xffff0000, v10
	v_lshlrev_b32_e32 v169, 16, v11
	v_lshlrev_b32_e32 v168, 16, v10
	v_and_b32_e32 v162, 0xffff0000, v11
	s_waitcnt vmcnt(27)
	v_lshlrev_b32_e32 v159, 16, v17
	v_lshlrev_b32_e32 v158, 16, v16
	v_and_b32_e32 v157, 0xffff0000, v17
	v_and_b32_e32 v156, 0xffff0000, v16
	s_waitcnt vmcnt(26)
	v_lshlrev_b32_e32 v153, 16, v21
	v_lshlrev_b32_e32 v152, 16, v20
	v_and_b32_e32 v151, 0xffff0000, v21
	v_and_b32_e32 v150, 0xffff0000, v20
	s_waitcnt vmcnt(25)
	v_lshlrev_b32_e32 v149, 16, v22
	v_and_b32_e32 v148, 0xffff0000, v22
	v_lshlrev_b32_e32 v117, 16, v23
	v_and_b32_e32 v115, 0xffff0000, v23
	s_waitcnt vmcnt(24)
	v_and_b32_e32 v140, 0xffff0000, v24
	v_lshlrev_b32_e32 v145, 16, v25
	v_lshlrev_b32_e32 v144, 16, v24
	v_and_b32_e32 v138, 0xffff0000, v25
	s_waitcnt vmcnt(23)
	v_lshlrev_b32_e32 v135, 16, v27
	v_lshlrev_b32_e32 v134, 16, v26
	v_and_b32_e32 v133, 0xffff0000, v27
	v_and_b32_e32 v132, 0xffff0000, v26
	s_waitcnt vmcnt(22)
	v_lshlrev_b32_e32 v129, 16, v29
	v_lshlrev_b32_e32 v128, 16, v28
	v_and_b32_e32 v127, 0xffff0000, v29
	v_and_b32_e32 v126, 0xffff0000, v28
	s_waitcnt vmcnt(21)
	v_lshlrev_b32_e32 v125, 16, v30
	v_and_b32_e32 v124, 0xffff0000, v30
	v_lshlrev_b32_e32 v7, 16, v31
	v_and_b32_e32 v5, 0xffff0000, v31
	s_waitcnt vmcnt(20)
	v_and_b32_e32 v116, 0xffff0000, v32
	v_lshlrev_b32_e32 v121, 16, v33
	v_lshlrev_b32_e32 v120, 16, v32
	v_and_b32_e32 v114, 0xffff0000, v33
	s_waitcnt vmcnt(19)
	v_lshlrev_b32_e32 v87, 16, v35
	v_lshlrev_b32_e32 v86, 16, v34
	v_and_b32_e32 v85, 0xffff0000, v35
	v_and_b32_e32 v84, 0xffff0000, v34
	s_waitcnt vmcnt(18)
	v_lshlrev_b32_e32 v41, 16, v37
	v_lshlrev_b32_e32 v40, 16, v36
	v_and_b32_e32 v39, 0xffff0000, v37
	v_and_b32_e32 v38, 0xffff0000, v36
	s_waitcnt vmcnt(17)
	v_lshlrev_b32_e32 v21, 16, v44
	v_and_b32_e32 v20, 0xffff0000, v44
	v_lshlrev_b32_e32 v187, 16, v45
	v_and_b32_e32 v186, 0xffff0000, v45
	s_waitcnt vmcnt(12)
	v_and_b32_e32 v6, 0xffff0000, v46
	v_lshlrev_b32_e32 v17, 16, v47
	v_lshlrev_b32_e32 v16, 16, v46
	v_and_b32_e32 v4, 0xffff0000, v47
	v_lshl_add_u64 v[8:9], s[16:17], 0, v[0:1]
	v_lshl_add_u64 v[0:1], s[18:19], 0, v[0:1]
	v_lshl_add_u64 v[10:11], s[48:49], 0, v[12:13]
	v_lshl_add_u64 v[12:13], s[38:39], 0, v[12:13]
	s_branch .LBB0_402
.LBB0_401:
	ds_read_b128 v[208:211], v249
	ds_read_b128 v[212:215], v249 offset:4096
	v_pk_add_f32 v[184:185], v[180:181], v[182:183]
	v_pk_mul_f32 v[216:217], v[182:183], v[182:183]
	v_pk_add_f32 v[218:219], v[176:177], v[178:179]
	v_pk_mul_f32 v[220:221], v[178:179], v[178:179]
	v_mov_b32_e32 v165, v172
	v_add_f32_e32 v227, v185, v184
	v_pk_fma_f32 v[184:185], v[180:181], v[180:181], v[216:217]
	v_pk_add_f32 v[216:217], v[218:219], v[218:219] op_sel_hi:[1,0]
	v_pk_fma_f32 v[218:219], v[176:177], v[176:177], v[220:221]
	v_pk_add_f32 v[220:221], v[164:165], v[172:173]
	v_add_f32_e32 v163, v139, v141
	v_mul_f32_e32 v229, v139, v139
	v_mov_b32_e32 v226, v168
	v_add_f32_e32 v227, 0, v227
	v_pk_add_f32 v[184:185], v[184:185], v[184:185] op_sel_hi:[1,0]
	v_pk_add_f32 v[218:219], v[218:219], v[218:219] op_sel_hi:[1,0]
	v_mov_b32_e32 v165, v217
	v_mov_b32_e32 v220, v169
	v_mul_f32_e32 v222, v172, v172
	v_mul_f32_e32 v225, v141, v141
	v_mov_b32_e32 v224, v162
	v_pk_add_f32 v[216:217], v[164:165], v[226:227]
	v_pk_add_f32 v[220:221], v[162:163], v[220:221]
	v_mul_f32_e32 v184, v168, v168
	v_mul_f32_e32 v218, v164, v164
	v_mov_b32_e32 v163, v229
	v_pk_fma_f32 v[222:223], v[172:173], v[172:173], v[222:223] op_sel_hi:[1,1,0]
	v_pk_add_f32 v[216:217], v[220:221], v[216:217]
	v_pk_add_f32 v[184:185], v[218:219], v[184:185]
	v_pk_add_f32 v[218:219], v[162:163], v[224:225]
	v_mul_f32_e32 v228, v162, v162
	v_mul_f32_e32 v222, v169, v169
	v_add_f32_e32 v163, v216, v217
	v_mov_b32_e32 v229, v219
	v_pk_add_f32 v[216:217], v[228:229], v[222:223]
	v_add_f32_dpp v163, v163, v163 quad_perm:[1,0,3,2] row_mask:0xf bank_mask:0xf bound_ctrl:1
	v_pk_add_f32 v[184:185], v[216:217], v[184:185]
	s_add_i32 s30, s30, s2
	v_add_f32_dpp v163, v163, v163 quad_perm:[2,3,0,1] row_mask:0xf bank_mask:0xf bound_ctrl:1
	v_add_f32_e32 v165, v184, v185
	s_add_u32 s34, s11, s30
	v_add_f32_dpp v163, v163, v163 row_half_mirror row_mask:0xf bank_mask:0xf bound_ctrl:1
	v_add_f32_dpp v165, v165, v165 quad_perm:[1,0,3,2] row_mask:0xf bank_mask:0xf bound_ctrl:1
	s_addc_u32 s35, s5, 0
	v_add_f32_dpp v163, v163, v163 row_mirror row_mask:0xf bank_mask:0xf bound_ctrl:1
	s_or_b64 s[34:35], s[34:35], s[0:1]
	v_readlane_b32 s37, v163, 0
	v_readlane_b32 s31, v163, 16
	v_readlane_b32 s45, v163, 32
	v_readlane_b32 s33, v163, 48
	v_add_f32_dpp v163, v165, v165 quad_perm:[2,3,0,1] row_mask:0xf bank_mask:0xf bound_ctrl:1
	v_mov_b32_e32 v185, s31
	v_mov_b32_e32 v217, s33
	v_add_f32_dpp v163, v163, v163 row_half_mirror row_mask:0xf bank_mask:0xf bound_ctrl:1
	s_lshl_b64 s[34:35], s[34:35], 11
	s_nop 0
	v_add_f32_dpp v163, v163, v163 row_mirror row_mask:0xf bank_mask:0xf bound_ctrl:1
	s_nop 0
	v_readlane_b32 s31, v163, 16
	v_readlane_b32 s33, v163, 48
	v_readlane_b32 s36, v163, 0
	v_readlane_b32 s44, v163, 32
	v_mov_b32_e32 v184, s31
	v_mov_b32_e32 v216, s33
	v_pk_add_f32 v[184:185], s[36:37], v[184:185]
	v_pk_add_f32 v[216:217], s[44:45], v[216:217]
	s_or_b32 s31, s30, 1
	v_pk_add_f32 v[184:185], v[184:185], v[216:217]
	s_waitcnt vmcnt(11)
	v_lshlrev_b32_e32 v216, 16, v155
	v_pk_mul_f32 v[184:185], v[184:185], s[4:5] op_sel_hi:[1,0]
	v_and_b32_e32 v217, 0xffff0000, v155
	v_fma_f32 v163, -v185, v185, v184
	v_max_f32_e32 v163, 0, v163
	v_add_f32_e32 v163, 0x358637bd, v163
	v_mul_f32_e32 v165, 0x4b800000, v163
	v_cmp_gt_f32_e32 vcc, s13, v163
	v_sub_f32_e32 v180, v180, v185
	v_sub_f32_e32 v181, v181, v185
	v_cndmask_b32_e32 v163, v163, v165, vcc
	v_rsq_f32_e32 v163, v163
	v_sub_f32_e32 v165, v182, v185
	v_sub_f32_e32 v178, v178, v185
	v_sub_f32_e32 v176, v176, v185
	v_mul_f32_e32 v182, 0x45800000, v163
	v_cndmask_b32_e32 v163, v163, v182, vcc
	v_mul_f32_e32 v165, v165, v163
	s_waitcnt vmcnt(0) lgkmcnt(0)
	v_fma_f32 v165, v165, v208, v212
	v_mul_f32_e32 v182, 0xbfb8aa3b, v165
	v_exp_f32_e32 v182, v182
	v_mul_f32_e32 v180, v180, v163
	v_fma_f32 v180, v180, v209, v213
	v_mul_f32_e32 v184, 0xbfb8aa3b, v180
	v_add_f32_e32 v182, 1.0, v182
	v_rcp_f32_e32 v182, v182
	v_exp_f32_e32 v184, v184
	v_mul_f32_e32 v181, v181, v163
	v_fmac_f32_e32 v215, v181, v211
	v_mul_f32_e32 v165, v165, v182
	v_lshlrev_b32_e32 v182, 16, v174
	v_mul_f32_e32 v165, v165, v182
	v_sub_f32_e32 v182, v183, v185
	v_mul_f32_e32 v182, v182, v163
	v_add_f32_e32 v184, 1.0, v184
	v_fma_f32 v182, v182, v210, v214
	v_rcp_f32_e32 v184, v184
	v_mul_f32_e32 v183, 0xbfb8aa3b, v182
	v_mul_f32_e32 v181, 0xbfb8aa3b, v215
	v_exp_f32_e32 v183, v183
	v_exp_f32_e32 v181, v181
	v_mul_f32_e32 v180, v180, v184
	v_and_b32_e32 v174, 0xffff0000, v174
	v_add_f32_e32 v183, 1.0, v183
	v_mul_f32_e32 v174, v180, v174
	v_add_f32_e32 v180, 1.0, v181
	v_rcp_f32_e32 v183, v183
	v_rcp_f32_e32 v180, v180
	v_sub_f32_e32 v179, v179, v185
	v_sub_f32_e32 v177, v177, v185
	v_mul_f32_e32 v181, v182, v183
	v_lshlrev_b32_e32 v182, 16, v175
	v_mul_f32_e32 v180, v215, v180
	v_and_b32_e32 v175, 0xffff0000, v175
	v_mul_f32_e32 v181, v181, v182
	v_mul_f32_e32 v175, v180, v175
	v_cvt_pk_bf16_f32 v180, v165, v174
	v_cvt_pk_bf16_f32 v181, v181, v175
	v_lshl_add_u64 v[174:175], v[12:13], 0, s[34:35]
	global_store_dwordx2 v[174:175], v[180:181], off
	ds_read_b128 v[180:183], v249 offset:1024
	s_nop 0
	ds_read_b128 v[208:211], v249 offset:5120
	v_mul_f32_e32 v178, v178, v163
	v_mul_f32_e32 v176, v176, v163
	v_mul_f32_e32 v179, v179, v163
	v_mul_f32_e32 v177, v177, v163
	v_lshlrev_b32_e32 v165, 16, v170
	v_and_b32_e32 v170, 0xffff0000, v170
	v_lshlrev_b32_e32 v184, 16, v171
	v_and_b32_e32 v171, 0xffff0000, v171
	v_sub_f32_e32 v172, v172, v185
	v_sub_f32_e32 v139, v139, v185
	v_sub_f32_e32 v141, v141, v185
	v_mul_f32_e32 v172, v172, v163
	v_mul_f32_e32 v139, v139, v163
	v_mul_f32_e32 v141, v141, v163
	v_sub_f32_e32 v164, v164, v185
	v_sub_f32_e32 v162, v162, v185
	v_mul_f32_e32 v164, v164, v163
	v_mul_f32_e32 v162, v162, v163
	v_mul_f32_e32 v214, v115, v115
	v_mul_f32_e32 v213, v117, v117
	v_mov_b32_e32 v212, v138
	v_and_b32_e32 v215, 0xffff0000, v154
	s_add_u32 s34, s11, s31
	s_addc_u32 s35, s5, 0
	s_or_b64 s[34:35], s[34:35], s[0:1]
	s_lshl_b64 s[34:35], s[34:35], 11
	s_waitcnt lgkmcnt(0)
	v_fma_f32 v178, v178, v180, v208
	v_fma_f32 v176, v176, v181, v209
	v_fma_f32 v179, v179, v182, v210
	v_fmac_f32_e32 v211, v177, v183
	v_mul_f32_e32 v177, 0xbfb8aa3b, v178
	v_mul_f32_e32 v180, 0xbfb8aa3b, v176
	v_mul_f32_e32 v181, 0xbfb8aa3b, v179
	v_mul_f32_e32 v182, 0xbfb8aa3b, v211
	v_exp_f32_e32 v177, v177
	v_exp_f32_e32 v180, v180
	v_exp_f32_e32 v181, v181
	v_exp_f32_e32 v182, v182
	v_add_f32_e32 v177, 1.0, v177
	v_add_f32_e32 v180, 1.0, v180
	v_add_f32_e32 v181, 1.0, v181
	v_add_f32_e32 v182, 1.0, v182
	v_rcp_f32_e32 v177, v177
	v_rcp_f32_e32 v180, v180
	v_rcp_f32_e32 v181, v181
	v_rcp_f32_e32 v182, v182
	v_mul_f32_e32 v177, v178, v177
	v_mul_f32_e32 v176, v176, v180
	v_mul_f32_e32 v178, v179, v181
	v_mul_f32_e32 v179, v211, v182
	v_mul_f32_e32 v170, v176, v170
	v_mul_f32_e32 v171, v179, v171
	v_mul_f32_e32 v165, v177, v165
	v_mul_f32_e32 v176, v178, v184
	v_cvt_pk_bf16_f32 v170, v165, v170
	v_cvt_pk_bf16_f32 v171, v176, v171
	global_store_dwordx2 v[174:175], v[170:171], off offset:512
	ds_read_b128 v[176:179], v249 offset:2048
	ds_read_b128 v[180:183], v249 offset:6144
	v_sub_f32_e32 v171, v173, v185
	v_mul_f32_e32 v171, v171, v163
	v_lshlrev_b32_e32 v170, 16, v167
	v_and_b32_e32 v167, 0xffff0000, v167
	v_lshlrev_b32_e32 v165, 16, v166
	v_and_b32_e32 v166, 0xffff0000, v166
	v_pk_add_f32 v[208:209], v[150:151], v[152:153]
	v_pk_mul_f32 v[210:211], v[152:153], v[152:153]
	v_mul_f32_e32 v184, v148, v148
	s_waitcnt lgkmcnt(0)
	v_fma_f32 v171, v171, v176, v180
	v_fma_f32 v172, v172, v177, v181
	v_fmac_f32_e32 v183, v139, v179
	v_fma_f32 v141, v141, v178, v182
	v_mul_f32_e32 v139, 0xbfb8aa3b, v171
	v_mul_f32_e32 v173, 0xbfb8aa3b, v172
	v_mul_f32_e32 v177, 0xbfb8aa3b, v183
	v_mul_f32_e32 v176, 0xbfb8aa3b, v141
	v_exp_f32_e32 v139, v139
	v_exp_f32_e32 v173, v173
	v_exp_f32_e32 v177, v177
	v_exp_f32_e32 v176, v176
	v_add_f32_e32 v139, 1.0, v139
	v_add_f32_e32 v173, 1.0, v173
	v_add_f32_e32 v177, 1.0, v177
	v_add_f32_e32 v176, 1.0, v176
	v_rcp_f32_e32 v139, v139
	v_rcp_f32_e32 v173, v173
	v_rcp_f32_e32 v177, v177
	v_rcp_f32_e32 v176, v176
	v_mul_f32_e32 v139, v171, v139
	v_mul_f32_e32 v171, v172, v173
	v_mul_f32_e32 v172, v183, v177
	v_mul_f32_e32 v141, v141, v176
	v_mul_f32_e32 v167, v172, v167
	v_mul_f32_e32 v139, v139, v165
	v_mul_f32_e32 v165, v171, v166
	v_mul_f32_e32 v141, v141, v170
	v_cvt_pk_bf16_f32 v166, v139, v165
	v_cvt_pk_bf16_f32 v167, v141, v167
	global_store_dwordx2 v[174:175], v[166:167], off offset:1024
	ds_read_b128 v[170:173], v249 offset:3072
	ds_read_b128 v[176:179], v249 offset:7168
	v_sub_f32_e32 v167, v168, v185
	v_sub_f32_e32 v168, v169, v185
	v_mul_f32_e32 v167, v167, v163
	v_mul_f32_e32 v168, v168, v163
	v_lshlrev_b32_e32 v165, 16, v160
	v_and_b32_e32 v160, 0xffff0000, v160
	v_lshlrev_b32_e32 v166, 16, v161
	v_and_b32_e32 v161, 0xffff0000, v161
	v_pk_add_f32 v[180:181], v[156:157], v[158:159]
	v_mov_b32_e32 v141, v148
	v_pk_mul_f32 v[182:183], v[158:159], v[158:159]
	v_add_f32_e32 v139, v115, v117
	v_lshlrev_b32_e32 v185, 16, v154
	v_pk_fma_f32 v[154:155], v[156:157], v[156:157], v[182:183]
	v_mov_b64_e32 v[182:183], v[60:61]
	v_pk_add_f32 v[154:155], v[154:155], v[154:155] op_sel_hi:[1,0]
	s_waitcnt lgkmcnt(0)
	v_fma_f32 v163, v167, v170, v176
	v_fma_f32 v164, v164, v171, v177
	v_fma_f32 v167, v168, v172, v178
	v_fmac_f32_e32 v179, v162, v173
	v_mul_f32_e32 v162, 0xbfb8aa3b, v163
	v_mul_f32_e32 v168, 0xbfb8aa3b, v164
	v_mul_f32_e32 v169, 0xbfb8aa3b, v167
	v_mul_f32_e32 v170, 0xbfb8aa3b, v179
	v_exp_f32_e32 v162, v162
	v_exp_f32_e32 v168, v168
	v_exp_f32_e32 v169, v169
	v_exp_f32_e32 v170, v170
	v_add_f32_e32 v162, 1.0, v162
	v_add_f32_e32 v168, 1.0, v168
	v_add_f32_e32 v169, 1.0, v169
	v_add_f32_e32 v170, 1.0, v170
	v_rcp_f32_e32 v162, v162
	v_rcp_f32_e32 v168, v168
	v_rcp_f32_e32 v169, v169
	v_rcp_f32_e32 v170, v170
	v_mul_f32_e32 v162, v163, v162
	v_mul_f32_e32 v163, v164, v168
	v_mul_f32_e32 v164, v167, v169
	v_mul_f32_e32 v167, v179, v170
	v_mul_f32_e32 v160, v163, v160
	v_mul_f32_e32 v161, v167, v161
	v_mul_f32_e32 v162, v162, v165
	v_mul_f32_e32 v163, v164, v166
	v_cvt_pk_bf16_f32 v160, v162, v160
	v_cvt_pk_bf16_f32 v161, v163, v161
	global_store_dwordx2 v[174:175], v[160:161], off offset:1536
	ds_read_b128 v[162:165], v249
	ds_read_b128 v[166:169], v249 offset:4096
	v_add_f32_e32 v161, v181, v180
	v_pk_add_f32 v[172:173], v[208:209], v[208:209] op_sel_hi:[1,0]
	v_pk_add_f32 v[176:177], v[140:141], v[148:149]
	v_mov_b32_e32 v160, v144
	v_add_f32_e32 v161, 0, v161
	v_mov_b32_e32 v141, v173
	v_mov_b32_e32 v176, v145
	v_pk_fma_f32 v[174:175], v[150:151], v[150:151], v[210:211]
	v_pk_add_f32 v[160:161], v[140:141], v[160:161]
	v_pk_add_f32 v[172:173], v[138:139], v[176:177]
	v_mov_b32_e32 v139, v214
	v_pk_fma_f32 v[178:179], v[148:149], v[148:149], v[184:185] op_sel_hi:[1,1,0]
	v_pk_add_f32 v[174:175], v[174:175], v[174:175] op_sel_hi:[1,0]
	v_pk_add_f32 v[160:161], v[172:173], v[160:161]
	v_pk_add_f32 v[172:173], v[138:139], v[212:213]
	v_mul_f32_e32 v170, v138, v138
	v_mul_f32_e32 v178, v145, v145
	v_mul_f32_e32 v154, v144, v144
	v_mul_f32_e32 v174, v140, v140
	v_add_f32_e32 v139, v160, v161
	v_mov_b32_e32 v171, v173
	v_pk_add_f32 v[154:155], v[174:175], v[154:155]
	v_pk_add_f32 v[160:161], v[170:171], v[178:179]
	v_add_f32_dpp v139, v139, v139 quad_perm:[1,0,3,2] row_mask:0xf bank_mask:0xf bound_ctrl:1
	v_pk_add_f32 v[154:155], v[160:161], v[154:155]
	v_mov_b64_e32 v[174:175], v[28:29]
	v_add_f32_dpp v139, v139, v139 quad_perm:[2,3,0,1] row_mask:0xf bank_mask:0xf bound_ctrl:1
	v_add_f32_e32 v141, v154, v155
	v_lshl_add_u64 v[154:155], v[12:13], 0, s[34:35]
	v_add_f32_dpp v139, v139, v139 row_half_mirror row_mask:0xf bank_mask:0xf bound_ctrl:1
	v_add_f32_dpp v141, v141, v141 quad_perm:[1,0,3,2] row_mask:0xf bank_mask:0xf bound_ctrl:1
	v_mov_b64_e32 v[176:177], v[68:69]
	v_add_f32_dpp v139, v139, v139 row_mirror row_mask:0xf bank_mask:0xf bound_ctrl:1
	v_mov_b64_e32 v[178:179], v[62:63]
	v_readlane_b32 s35, v139, 0
	v_readlane_b32 s31, v139, 16
	v_readlane_b32 s37, v139, 32
	v_readlane_b32 s33, v139, 48
	v_add_f32_dpp v139, v141, v141 quad_perm:[2,3,0,1] row_mask:0xf bank_mask:0xf bound_ctrl:1
	v_mov_b32_e32 v161, s31
	v_mov_b32_e32 v171, s33
	v_add_f32_dpp v139, v139, v139 row_half_mirror row_mask:0xf bank_mask:0xf bound_ctrl:1
	v_mov_b64_e32 v[180:181], v[66:67]
	v_mov_b32_e32 v172, v188
	v_add_f32_dpp v139, v139, v139 row_mirror row_mask:0xf bank_mask:0xf bound_ctrl:1
	v_mov_b32_e32 v173, v64
	v_readlane_b32 s31, v139, 16
	v_readlane_b32 s33, v139, 48
	v_readlane_b32 s34, v139, 0
	v_readlane_b32 s36, v139, 32
	v_mov_b32_e32 v160, s31
	v_mov_b32_e32 v170, s33
	v_pk_add_f32 v[160:161], s[34:35], v[160:161]
	v_pk_add_f32 v[170:171], s[36:37], v[170:171]
	s_or_b32 s31, s30, 2
	v_pk_add_f32 v[160:161], v[160:161], v[170:171]
	v_lshlrev_b32_e32 v170, 16, v131
	v_pk_mul_f32 v[160:161], v[160:161], s[4:5] op_sel_hi:[1,0]
	v_and_b32_e32 v171, 0xffff0000, v131
	v_fma_f32 v139, -v161, v161, v160
	v_max_f32_e32 v139, 0, v139
	v_add_f32_e32 v139, 0x358637bd, v139
	v_sub_f32_e32 v141, v158, v161
	v_mul_f32_e32 v158, 0x4b800000, v139
	v_cmp_gt_f32_e32 vcc, s13, v139
	v_sub_f32_e32 v156, v156, v161
	v_sub_f32_e32 v157, v157, v161
	v_cndmask_b32_e32 v139, v139, v158, vcc
	v_rsq_f32_e32 v139, v139
	v_sub_f32_e32 v158, v159, v161
	v_sub_f32_e32 v152, v152, v161
	v_sub_f32_e32 v150, v150, v161
	v_mul_f32_e32 v159, 0x45800000, v139
	v_cndmask_b32_e32 v139, v139, v159, vcc
	v_mul_f32_e32 v141, v141, v139
	v_mul_f32_e32 v156, v156, v139
	v_mul_f32_e32 v158, v158, v139
	v_mul_f32_e32 v157, v157, v139
	v_sub_f32_e32 v153, v153, v161
	s_waitcnt lgkmcnt(0)
	v_fma_f32 v141, v141, v162, v166
	v_fma_f32 v156, v156, v163, v167
	v_fma_f32 v158, v158, v164, v168
	v_fmac_f32_e32 v169, v157, v165
	v_mul_f32_e32 v157, 0xbfb8aa3b, v141
	v_mul_f32_e32 v159, 0xbfb8aa3b, v156
	v_mul_f32_e32 v160, 0xbfb8aa3b, v158
	v_mul_f32_e32 v162, 0xbfb8aa3b, v169
	v_exp_f32_e32 v157, v157
	v_exp_f32_e32 v159, v159
	v_exp_f32_e32 v160, v160
	v_exp_f32_e32 v162, v162
	v_add_f32_e32 v157, 1.0, v157
	v_add_f32_e32 v159, 1.0, v159
	v_add_f32_e32 v160, 1.0, v160
	v_add_f32_e32 v162, 1.0, v162
	v_rcp_f32_e32 v157, v157
	v_rcp_f32_e32 v159, v159
	v_rcp_f32_e32 v160, v160
	v_rcp_f32_e32 v162, v162
	v_mul_f32_e32 v141, v141, v157
	v_mul_f32_e32 v156, v156, v159
	v_mul_f32_e32 v157, v158, v160
	v_mul_f32_e32 v158, v169, v162
	v_mul_f32_e32 v156, v156, v215
	v_mul_f32_e32 v157, v157, v216
	v_mul_f32_e32 v141, v141, v185
	v_mul_f32_e32 v158, v158, v217
	v_cvt_pk_bf16_f32 v156, v141, v156
	v_cvt_pk_bf16_f32 v157, v157, v158
	global_store_dwordx2 v[154:155], v[156:157], off
	ds_read_b128 v[156:159], v249 offset:1024
	s_nop 0
	ds_read_b128 v[162:165], v249 offset:5120
	v_sub_f32_e32 v151, v151, v161
	v_mul_f32_e32 v152, v152, v139
	v_mul_f32_e32 v150, v150, v139
	v_mul_f32_e32 v153, v153, v139
	v_mul_f32_e32 v151, v151, v139
	v_lshlrev_b32_e32 v141, 16, v146
	v_and_b32_e32 v146, 0xffff0000, v146
	v_lshlrev_b32_e32 v160, 16, v147
	v_and_b32_e32 v147, 0xffff0000, v147
	v_sub_f32_e32 v148, v148, v161
	v_sub_f32_e32 v115, v115, v161
	v_sub_f32_e32 v117, v117, v161
	v_mul_f32_e32 v148, v148, v139
	v_mul_f32_e32 v115, v115, v139
	v_mul_f32_e32 v117, v117, v139
	v_sub_f32_e32 v140, v140, v161
	v_sub_f32_e32 v138, v138, v161
	v_mul_f32_e32 v140, v140, v139
	v_mul_f32_e32 v138, v138, v139
	v_mul_f32_e32 v168, v5, v5
	v_mul_f32_e32 v167, v7, v7
	v_mov_b32_e32 v166, v114
	v_and_b32_e32 v169, 0xffff0000, v130
	s_add_u32 s34, s11, s31
	s_addc_u32 s35, s5, 0
	s_or_b64 s[34:35], s[34:35], s[0:1]
	s_lshl_b64 s[34:35], s[34:35], 11
	v_lshlrev_b32_e32 v216, 16, v3
	v_and_b32_e32 v217, 0xffff0000, v3
	s_waitcnt lgkmcnt(0)
	v_fma_f32 v152, v152, v156, v162
	v_fma_f32 v150, v150, v157, v163
	v_fma_f32 v153, v153, v158, v164
	v_fmac_f32_e32 v165, v151, v159
	v_mul_f32_e32 v151, 0xbfb8aa3b, v152
	v_mul_f32_e32 v156, 0xbfb8aa3b, v150
	v_mul_f32_e32 v157, 0xbfb8aa3b, v153
	v_mul_f32_e32 v158, 0xbfb8aa3b, v165
	v_exp_f32_e32 v151, v151
	v_exp_f32_e32 v156, v156
	v_exp_f32_e32 v157, v157
	v_exp_f32_e32 v158, v158
	v_add_f32_e32 v151, 1.0, v151
	v_add_f32_e32 v156, 1.0, v156
	v_add_f32_e32 v157, 1.0, v157
	v_add_f32_e32 v158, 1.0, v158
	v_rcp_f32_e32 v151, v151
	v_rcp_f32_e32 v156, v156
	v_rcp_f32_e32 v157, v157
	v_rcp_f32_e32 v158, v158
	v_mul_f32_e32 v151, v152, v151
	v_mul_f32_e32 v150, v150, v156
	v_mul_f32_e32 v152, v153, v157
	v_mul_f32_e32 v153, v165, v158
	v_mul_f32_e32 v146, v150, v146
	v_mul_f32_e32 v147, v153, v147
	v_mul_f32_e32 v141, v151, v141
	v_mul_f32_e32 v150, v152, v160
	v_cvt_pk_bf16_f32 v146, v141, v146
	v_cvt_pk_bf16_f32 v147, v150, v147
	global_store_dwordx2 v[154:155], v[146:147], off offset:512
	ds_read_b128 v[150:153], v249 offset:2048
	ds_read_b128 v[156:159], v249 offset:6144
	v_sub_f32_e32 v147, v149, v161
	v_mul_f32_e32 v147, v147, v139
	v_lshlrev_b32_e32 v146, 16, v143
	v_and_b32_e32 v143, 0xffff0000, v143
	v_lshlrev_b32_e32 v141, 16, v142
	v_and_b32_e32 v142, 0xffff0000, v142
	v_pk_add_f32 v[162:163], v[126:127], v[128:129]
	v_pk_mul_f32 v[164:165], v[128:129], v[128:129]
	v_mul_f32_e32 v160, v124, v124
	s_waitcnt lgkmcnt(0)
	v_fma_f32 v147, v147, v150, v156
	v_fma_f32 v148, v148, v151, v157
	v_fmac_f32_e32 v159, v115, v153
	v_fma_f32 v117, v117, v152, v158
	v_mul_f32_e32 v115, 0xbfb8aa3b, v147
	v_mul_f32_e32 v149, 0xbfb8aa3b, v148
	v_mul_f32_e32 v151, 0xbfb8aa3b, v159
	v_mul_f32_e32 v150, 0xbfb8aa3b, v117
	v_exp_f32_e32 v115, v115
	v_exp_f32_e32 v149, v149
	v_exp_f32_e32 v151, v151
	v_exp_f32_e32 v150, v150
	v_add_f32_e32 v115, 1.0, v115
	v_add_f32_e32 v149, 1.0, v149
	v_add_f32_e32 v151, 1.0, v151
	v_add_f32_e32 v150, 1.0, v150
	v_rcp_f32_e32 v115, v115
	v_rcp_f32_e32 v149, v149
	v_rcp_f32_e32 v151, v151
	v_rcp_f32_e32 v150, v150
	v_mul_f32_e32 v115, v147, v115
	v_mul_f32_e32 v147, v148, v149
	v_mul_f32_e32 v148, v159, v151
	v_mul_f32_e32 v117, v117, v150
	v_mul_f32_e32 v143, v148, v143
	v_mul_f32_e32 v115, v115, v141
	v_mul_f32_e32 v141, v147, v142
	v_mul_f32_e32 v117, v117, v146
	v_cvt_pk_bf16_f32 v142, v115, v141
	v_cvt_pk_bf16_f32 v143, v117, v143
	global_store_dwordx2 v[154:155], v[142:143], off offset:1024
	ds_read_b128 v[146:149], v249 offset:3072
	ds_read_b128 v[150:153], v249 offset:7168
	v_sub_f32_e32 v143, v144, v161
	v_sub_f32_e32 v144, v145, v161
	v_mul_f32_e32 v143, v143, v139
	v_mul_f32_e32 v144, v144, v139
	v_lshlrev_b32_e32 v141, 16, v136
	v_and_b32_e32 v136, 0xffff0000, v136
	v_lshlrev_b32_e32 v142, 16, v137
	v_and_b32_e32 v137, 0xffff0000, v137
	v_pk_add_f32 v[156:157], v[132:133], v[134:135]
	v_mov_b32_e32 v117, v124
	v_pk_mul_f32 v[158:159], v[134:135], v[134:135]
	v_add_f32_e32 v115, v5, v7
	v_lshlrev_b32_e32 v161, 16, v130
	v_pk_fma_f32 v[130:131], v[132:133], v[132:133], v[158:159]
	v_mov_b64_e32 v[158:159], v[72:73]
	v_pk_add_f32 v[130:131], v[130:131], v[130:131] op_sel_hi:[1,0]
	s_waitcnt lgkmcnt(0)
	v_fma_f32 v139, v143, v146, v150
	v_fma_f32 v140, v140, v147, v151
	v_fma_f32 v143, v144, v148, v152
	v_fmac_f32_e32 v153, v138, v149
	v_mul_f32_e32 v138, 0xbfb8aa3b, v139
	v_mul_f32_e32 v144, 0xbfb8aa3b, v140
	v_mul_f32_e32 v145, 0xbfb8aa3b, v143
	v_mul_f32_e32 v146, 0xbfb8aa3b, v153
	v_exp_f32_e32 v138, v138
	v_exp_f32_e32 v144, v144
	v_exp_f32_e32 v145, v145
	v_exp_f32_e32 v146, v146
	v_add_f32_e32 v138, 1.0, v138
	v_add_f32_e32 v144, 1.0, v144
	v_add_f32_e32 v145, 1.0, v145
	v_add_f32_e32 v146, 1.0, v146
	v_rcp_f32_e32 v138, v138
	v_rcp_f32_e32 v144, v144
	v_rcp_f32_e32 v145, v145
	v_rcp_f32_e32 v146, v146
	v_mul_f32_e32 v138, v139, v138
	v_mul_f32_e32 v139, v140, v144
	v_mul_f32_e32 v140, v143, v145
	v_mul_f32_e32 v143, v153, v146
	v_mul_f32_e32 v136, v139, v136
	v_mul_f32_e32 v137, v143, v137
	v_mul_f32_e32 v138, v138, v141
	v_mul_f32_e32 v139, v140, v142
	v_cvt_pk_bf16_f32 v136, v138, v136
	v_cvt_pk_bf16_f32 v137, v139, v137
	global_store_dwordx2 v[154:155], v[136:137], off offset:1536
	ds_read_b128 v[138:141], v249
	ds_read_b128 v[142:145], v249 offset:4096
	v_add_f32_e32 v137, v157, v156
	v_pk_add_f32 v[148:149], v[162:163], v[162:163] op_sel_hi:[1,0]
	v_pk_add_f32 v[152:153], v[116:117], v[124:125]
	v_mov_b32_e32 v136, v120
	v_add_f32_e32 v137, 0, v137
	v_mov_b32_e32 v117, v149
	v_mov_b32_e32 v152, v121
	v_pk_fma_f32 v[150:151], v[126:127], v[126:127], v[164:165]
	v_pk_add_f32 v[136:137], v[116:117], v[136:137]
	v_pk_add_f32 v[148:149], v[114:115], v[152:153]
	v_mov_b32_e32 v115, v168
	v_pk_fma_f32 v[154:155], v[124:125], v[124:125], v[160:161] op_sel_hi:[1,1,0]
	v_pk_add_f32 v[150:151], v[150:151], v[150:151] op_sel_hi:[1,0]
	v_pk_add_f32 v[136:137], v[148:149], v[136:137]
	v_pk_add_f32 v[148:149], v[114:115], v[166:167]
	v_mul_f32_e32 v146, v114, v114
	v_mul_f32_e32 v154, v121, v121
	v_mul_f32_e32 v130, v120, v120
	v_mul_f32_e32 v150, v116, v116
	v_add_f32_e32 v115, v136, v137
	v_mov_b32_e32 v147, v149
	v_pk_add_f32 v[130:131], v[150:151], v[130:131]
	v_pk_add_f32 v[136:137], v[146:147], v[154:155]
	v_add_f32_dpp v115, v115, v115 quad_perm:[1,0,3,2] row_mask:0xf bank_mask:0xf bound_ctrl:1
	v_pk_add_f32 v[130:131], v[136:137], v[130:131]
	v_and_b32_e32 v165, 0xffff0000, v2
	v_add_f32_dpp v115, v115, v115 quad_perm:[2,3,0,1] row_mask:0xf bank_mask:0xf bound_ctrl:1
	v_add_f32_e32 v117, v130, v131
	v_lshl_add_u64 v[130:131], v[12:13], 0, s[34:35]
	v_add_f32_dpp v115, v115, v115 row_half_mirror row_mask:0xf bank_mask:0xf bound_ctrl:1
	v_add_f32_dpp v117, v117, v117 quad_perm:[1,0,3,2] row_mask:0xf bank_mask:0xf bound_ctrl:1
	v_mov_b64_e32 v[154:155], v[36:37]
	v_add_f32_dpp v115, v115, v115 row_mirror row_mask:0xf bank_mask:0xf bound_ctrl:1
	v_mov_b64_e32 v[166:167], v[24:25]
	v_readlane_b32 s37, v115, 0
	v_readlane_b32 s31, v115, 16
	v_readlane_b32 s45, v115, 32
	v_readlane_b32 s33, v115, 48
	v_add_f32_dpp v115, v117, v117 quad_perm:[2,3,0,1] row_mask:0xf bank_mask:0xf bound_ctrl:1
	v_mov_b32_e32 v137, s31
	v_mov_b32_e32 v147, s33
	v_add_f32_dpp v115, v115, v115 row_half_mirror row_mask:0xf bank_mask:0xf bound_ctrl:1
	v_mov_b32_e32 v162, v191
	v_mov_b32_e32 v164, v189
	v_add_f32_dpp v115, v115, v115 row_mirror row_mask:0xf bank_mask:0xf bound_ctrl:1
	v_mov_b64_e32 v[150:151], v[90:91]
	v_readlane_b32 s31, v115, 16
	v_readlane_b32 s33, v115, 48
	v_readlane_b32 s36, v115, 0
	v_readlane_b32 s44, v115, 32
	v_mov_b32_e32 v136, s31
	v_mov_b32_e32 v146, s33
	v_pk_add_f32 v[136:137], s[36:37], v[136:137]
	v_pk_add_f32 v[146:147], s[44:45], v[146:147]
	s_or_b32 s36, s30, 3
	v_pk_add_f32 v[136:137], v[136:137], v[146:147]
	s_add_u32 s36, s11, s36
	v_pk_mul_f32 v[136:137], v[136:137], s[4:5] op_sel_hi:[1,0]
	s_addc_u32 s37, s5, 0
	v_fma_f32 v115, -v137, v137, v136
	v_max_f32_e32 v115, 0, v115
	v_add_f32_e32 v115, 0x358637bd, v115
	v_sub_f32_e32 v117, v134, v137
	v_mul_f32_e32 v134, 0x4b800000, v115
	v_cmp_gt_f32_e32 vcc, s13, v115
	v_sub_f32_e32 v133, v133, v137
	v_sub_f32_e32 v132, v132, v137
	v_cndmask_b32_e32 v115, v115, v134, vcc
	v_rsq_f32_e32 v115, v115
	v_sub_f32_e32 v134, v135, v137
	v_sub_f32_e32 v128, v128, v137
	v_sub_f32_e32 v129, v129, v137
	v_mul_f32_e32 v135, 0x45800000, v115
	v_cndmask_b32_e32 v146, v115, v135, vcc
	v_mul_f32_e32 v115, v117, v146
	v_mul_f32_e32 v133, v133, v146
	v_mul_f32_e32 v117, v132, v146
	v_mul_f32_e32 v132, v134, v146
	v_sub_f32_e32 v127, v127, v137
	s_waitcnt lgkmcnt(0)
	v_fma_f32 v115, v115, v138, v142
	v_fmac_f32_e32 v145, v133, v141
	v_fma_f32 v117, v117, v139, v143
	v_fma_f32 v132, v132, v140, v144
	v_mul_f32_e32 v133, 0xbfb8aa3b, v115
	v_mul_f32_e32 v136, 0xbfb8aa3b, v145
	v_mul_f32_e32 v134, 0xbfb8aa3b, v117
	v_mul_f32_e32 v135, 0xbfb8aa3b, v132
	v_exp_f32_e32 v133, v133
	v_exp_f32_e32 v136, v136
	v_exp_f32_e32 v134, v134
	v_exp_f32_e32 v135, v135
	v_add_f32_e32 v133, 1.0, v133
	v_add_f32_e32 v136, 1.0, v136
	v_add_f32_e32 v134, 1.0, v134
	v_add_f32_e32 v135, 1.0, v135
	v_rcp_f32_e32 v133, v133
	v_rcp_f32_e32 v136, v136
	v_rcp_f32_e32 v134, v134
	v_rcp_f32_e32 v135, v135
	v_mul_f32_e32 v115, v115, v133
	v_mul_f32_e32 v133, v145, v136
	v_mul_f32_e32 v117, v117, v134
	v_mul_f32_e32 v132, v132, v135
	v_mul_f32_e32 v133, v133, v171
	v_mul_f32_e32 v115, v115, v161
	v_mul_f32_e32 v117, v117, v169
	v_mul_f32_e32 v134, v132, v170
	v_cvt_pk_bf16_f32 v132, v115, v117
	v_cvt_pk_bf16_f32 v133, v134, v133
	global_store_dwordx2 v[130:131], v[132:133], off
	ds_read_b128 v[132:135], v249 offset:1024
	s_nop 0
	ds_read_b128 v[138:141], v249 offset:5120
	v_sub_f32_e32 v126, v126, v137
	v_mul_f32_e32 v128, v128, v146
	v_mul_f32_e32 v129, v129, v146
	v_mul_f32_e32 v127, v127, v146
	v_mul_f32_e32 v126, v126, v146
	v_lshlrev_b32_e32 v115, 16, v122
	v_and_b32_e32 v117, 0xffff0000, v122
	v_lshlrev_b32_e32 v122, 16, v123
	v_and_b32_e32 v123, 0xffff0000, v123
	v_sub_f32_e32 v7, v7, v137
	v_sub_f32_e32 v5, v5, v137
	v_mul_f32_e32 v7, v7, v146
	v_mul_f32_e32 v5, v5, v146
	v_sub_f32_e32 v116, v116, v137
	v_sub_f32_e32 v114, v114, v137
	v_mul_f32_e32 v116, v116, v146
	v_mul_f32_e32 v114, v114, v146
	v_mul_f32_e32 v142, v186, v186
	v_mul_f32_e32 v136, v20, v20
	v_and_b32_e32 v143, 0xffff0000, v42
	v_lshlrev_b32_e32 v144, 16, v43
	v_and_b32_e32 v145, 0xffff0000, v43
	s_or_b64 s[36:37], s[36:37], s[0:1]
	s_add_i32 s12, s12, 4
	v_mov_b64_e32 v[160:161], v[22:23]
	v_mov_b64_e32 v[170:171], v[26:27]
	v_mov_b64_e32 v[152:153], v[74:75]
	v_mov_b64_e32 v[156:157], v[88:89]
	v_mov_b64_e32 v[168:169], v[70:71]
	v_mov_b32_e32 v148, v194
	v_mov_b32_e32 v149, v76
	s_waitcnt lgkmcnt(0)
	v_fma_f32 v128, v128, v132, v138
	v_fma_f32 v129, v129, v134, v140
	v_fmac_f32_e32 v141, v127, v135
	v_fma_f32 v126, v126, v133, v139
	v_mul_f32_e32 v127, 0xbfb8aa3b, v128
	v_mul_f32_e32 v133, 0xbfb8aa3b, v129
	v_mul_f32_e32 v134, 0xbfb8aa3b, v141
	v_mul_f32_e32 v132, 0xbfb8aa3b, v126
	v_exp_f32_e32 v127, v127
	v_exp_f32_e32 v133, v133
	v_exp_f32_e32 v134, v134
	v_exp_f32_e32 v132, v132
	v_add_f32_e32 v127, 1.0, v127
	v_add_f32_e32 v133, 1.0, v133
	v_add_f32_e32 v134, 1.0, v134
	v_add_f32_e32 v132, 1.0, v132
	v_rcp_f32_e32 v127, v127
	v_rcp_f32_e32 v133, v133
	v_rcp_f32_e32 v134, v134
	v_rcp_f32_e32 v132, v132
	v_mul_f32_e32 v127, v128, v127
	v_mul_f32_e32 v128, v129, v133
	v_mul_f32_e32 v129, v141, v134
	v_mul_f32_e32 v126, v126, v132
	v_mul_f32_e32 v123, v129, v123
	v_mul_f32_e32 v115, v127, v115
	v_mul_f32_e32 v117, v126, v117
	v_mul_f32_e32 v126, v128, v122
	v_cvt_pk_bf16_f32 v122, v115, v117
	v_cvt_pk_bf16_f32 v123, v126, v123
	global_store_dwordx2 v[130:131], v[122:123], off offset:512
	ds_read_b128 v[126:129], v249 offset:2048
	ds_read_b128 v[132:135], v249 offset:6144
	v_sub_f32_e32 v122, v125, v137
	v_sub_f32_e32 v123, v124, v137
	v_mul_f32_e32 v122, v122, v146
	v_mul_f32_e32 v123, v123, v146
	v_lshlrev_b32_e32 v115, 16, v118
	v_and_b32_e32 v117, 0xffff0000, v118
	v_lshlrev_b32_e32 v118, 16, v119
	v_and_b32_e32 v119, 0xffff0000, v119
	v_pk_add_f32 v[138:139], v[38:39], v[40:41]
	v_pk_mul_f32 v[140:141], v[40:41], v[40:41]
	s_waitcnt lgkmcnt(0)
	v_fma_f32 v122, v122, v126, v132
	v_fma_f32 v123, v123, v127, v133
	v_fma_f32 v7, v7, v128, v134
	v_fmac_f32_e32 v135, v5, v129
	v_mul_f32_e32 v5, 0xbfb8aa3b, v122
	v_mul_f32_e32 v124, 0xbfb8aa3b, v123
	v_mul_f32_e32 v125, 0xbfb8aa3b, v7
	v_mul_f32_e32 v126, 0xbfb8aa3b, v135
	v_exp_f32_e32 v5, v5
	v_exp_f32_e32 v124, v124
	v_exp_f32_e32 v125, v125
	v_exp_f32_e32 v126, v126
	v_add_f32_e32 v5, 1.0, v5
	v_add_f32_e32 v124, 1.0, v124
	v_add_f32_e32 v125, 1.0, v125
	v_add_f32_e32 v126, 1.0, v126
	v_rcp_f32_e32 v5, v5
	v_rcp_f32_e32 v124, v124
	v_rcp_f32_e32 v125, v125
	v_rcp_f32_e32 v126, v126
	v_mul_f32_e32 v5, v122, v5
	v_mul_f32_e32 v122, v123, v124
	v_mul_f32_e32 v7, v7, v125
	v_mul_f32_e32 v123, v135, v126
	v_mul_f32_e32 v5, v5, v115
	v_mul_f32_e32 v115, v122, v117
	v_mul_f32_e32 v7, v7, v118
	v_mul_f32_e32 v117, v123, v119
	v_cvt_pk_bf16_f32 v118, v5, v115
	v_cvt_pk_bf16_f32 v119, v7, v117
	global_store_dwordx2 v[130:131], v[118:119], off offset:1024
	ds_read_b128 v[122:125], v249 offset:3072
	ds_read_b128 v[126:129], v249 offset:7168
	v_sub_f32_e32 v119, v120, v137
	v_sub_f32_e32 v120, v121, v137
	v_mul_f32_e32 v119, v119, v146
	v_mul_f32_e32 v120, v120, v146
	v_lshlrev_b32_e32 v117, 16, v108
	v_and_b32_e32 v108, 0xffff0000, v108
	v_lshlrev_b32_e32 v118, 16, v109
	v_and_b32_e32 v109, 0xffff0000, v109
	v_pk_add_f32 v[132:133], v[84:85], v[86:87]
	v_mov_b32_e32 v7, v20
	v_pk_mul_f32 v[134:135], v[86:87], v[86:87]
	v_add_f32_e32 v5, v186, v187
	v_mul_f32_e32 v115, v187, v187
	v_lshlrev_b32_e32 v137, 16, v42
	v_pk_fma_f32 v[42:43], v[84:85], v[84:85], v[134:135]
	v_mov_b64_e32 v[146:147], v[34:35]
	v_pk_add_f32 v[42:43], v[42:43], v[42:43] op_sel_hi:[1,0]
	v_mov_b64_e32 v[134:135], v[80:81]
	v_mul_f32_e32 v42, v16, v16
	s_waitcnt lgkmcnt(0)
	v_fma_f32 v119, v119, v122, v126
	v_fma_f32 v116, v116, v123, v127
	v_fma_f32 v120, v120, v124, v128
	v_fmac_f32_e32 v129, v114, v125
	v_mul_f32_e32 v114, 0xbfb8aa3b, v119
	v_mul_f32_e32 v121, 0xbfb8aa3b, v116
	v_mul_f32_e32 v122, 0xbfb8aa3b, v120
	v_mul_f32_e32 v123, 0xbfb8aa3b, v129
	v_exp_f32_e32 v114, v114
	v_exp_f32_e32 v121, v121
	v_exp_f32_e32 v122, v122
	v_exp_f32_e32 v123, v123
	v_add_f32_e32 v114, 1.0, v114
	v_add_f32_e32 v121, 1.0, v121
	v_add_f32_e32 v122, 1.0, v122
	v_add_f32_e32 v123, 1.0, v123
	v_rcp_f32_e32 v114, v114
	v_rcp_f32_e32 v121, v121
	v_rcp_f32_e32 v122, v122
	v_rcp_f32_e32 v123, v123
	v_mul_f32_e32 v114, v119, v114
	v_mul_f32_e32 v116, v116, v121
	v_mul_f32_e32 v119, v120, v122
	v_mul_f32_e32 v120, v129, v123
	v_mul_f32_e32 v108, v116, v108
	v_mul_f32_e32 v109, v120, v109
	v_mul_f32_e32 v114, v114, v117
	v_mul_f32_e32 v116, v119, v118
	v_cvt_pk_bf16_f32 v108, v114, v108
	v_cvt_pk_bf16_f32 v109, v116, v109
	global_store_dwordx2 v[130:131], v[108:109], off offset:1536
	ds_read_b128 v[116:119], v249
	ds_read_b128 v[120:123], v249 offset:4096
	v_add_f32_e32 v109, v133, v132
	v_pk_add_f32 v[126:127], v[138:139], v[138:139] op_sel_hi:[1,0]
	v_pk_add_f32 v[130:131], v[6:7], v[20:21]
	v_mov_b32_e32 v108, v16
	v_add_f32_e32 v109, 0, v109
	v_mov_b32_e32 v7, v127
	v_mov_b32_e32 v130, v17
	v_mov_b32_e32 v114, v4
	v_pk_fma_f32 v[128:129], v[38:39], v[38:39], v[140:141]
	v_pk_add_f32 v[108:109], v[6:7], v[108:109]
	v_pk_add_f32 v[126:127], v[4:5], v[130:131]
	v_mov_b32_e32 v5, v142
	v_pk_fma_f32 v[132:133], v[20:21], v[20:21], v[136:137] op_sel_hi:[1,1,0]
	v_pk_add_f32 v[128:129], v[128:129], v[128:129] op_sel_hi:[1,0]
	v_pk_add_f32 v[108:109], v[126:127], v[108:109]
	v_pk_add_f32 v[114:115], v[4:5], v[114:115]
	v_mul_f32_e32 v124, v4, v4
	v_mul_f32_e32 v132, v17, v17
	v_mul_f32_e32 v128, v6, v6
	v_add_f32_e32 v5, v108, v109
	v_mov_b32_e32 v125, v115
	v_pk_add_f32 v[42:43], v[128:129], v[42:43]
	v_pk_add_f32 v[108:109], v[124:125], v[132:133]
	v_add_f32_dpp v5, v5, v5 quad_perm:[1,0,3,2] row_mask:0xf bank_mask:0xf bound_ctrl:1
	v_pk_add_f32 v[42:43], v[108:109], v[42:43]
	v_mov_b64_e32 v[130:131], v[50:51]
	v_add_f32_dpp v5, v5, v5 quad_perm:[2,3,0,1] row_mask:0xf bank_mask:0xf bound_ctrl:1
	v_add_f32_e32 v7, v42, v43
	v_mov_b32_e32 v138, v197
	v_add_f32_dpp v5, v5, v5 row_half_mirror row_mask:0xf bank_mask:0xf bound_ctrl:1
	v_add_f32_dpp v7, v7, v7 quad_perm:[1,0,3,2] row_mask:0xf bank_mask:0xf bound_ctrl:1
	v_mov_b32_e32 v140, v195
	v_add_f32_dpp v5, v5, v5 row_mirror row_mask:0xf bank_mask:0xf bound_ctrl:1
	v_mov_b32_e32 v139, v190
	v_readlane_b32 s31, v5, 0
	v_readlane_b32 s33, v5, 16
	v_readlane_b32 s35, v5, 32
	v_readlane_b32 s34, v5, 48
	v_add_f32_dpp v5, v7, v7 quad_perm:[2,3,0,1] row_mask:0xf bank_mask:0xf bound_ctrl:1
	v_mov_b32_e32 v43, s33
	v_mov_b32_e32 v109, s34
	v_add_f32_dpp v5, v5, v5 row_half_mirror row_mask:0xf bank_mask:0xf bound_ctrl:1
	v_mov_b32_e32 v141, v65
	v_mov_b64_e32 v[126:127], v[106:107]
	v_add_f32_dpp v5, v5, v5 row_mirror row_mask:0xf bank_mask:0xf bound_ctrl:1
	v_mov_b64_e32 v[128:129], v[82:83]
	v_readlane_b32 s33, v5, 16
	v_readlane_b32 s44, v5, 48
	v_readlane_b32 s30, v5, 0
	v_readlane_b32 s34, v5, 32
	v_mov_b32_e32 v42, s33
	v_mov_b32_e32 v108, s44
	v_pk_add_f32 v[42:43], s[30:31], v[42:43]
	v_pk_add_f32 v[108:109], s[34:35], v[108:109]
	s_lshl_b64 s[30:31], s[36:37], 11
	v_pk_add_f32 v[42:43], v[42:43], v[108:109]
	v_lshl_add_u64 v[184:185], v[12:13], 0, s[30:31]
	v_pk_mul_f32 v[114:115], v[42:43], s[4:5] op_sel_hi:[1,0]
	v_mov_b64_e32 v[108:109], v[44:45]
	v_fma_f32 v5, -v115, v115, v114
	v_max_f32_e32 v5, 0, v5
	v_add_f32_e32 v5, 0x358637bd, v5
	v_mul_f32_e32 v42, 0x4b800000, v5
	v_cmp_gt_f32_e32 vcc, s13, v5
	v_sub_f32_e32 v7, v86, v115
	v_sub_f32_e32 v43, v87, v115
	v_cndmask_b32_e32 v5, v5, v42, vcc
	v_rsq_f32_e32 v5, v5
	v_sub_f32_e32 v42, v84, v115
	v_sub_f32_e32 v84, v85, v115
	v_sub_f32_e32 v40, v40, v115
	v_mul_f32_e32 v85, 0x45800000, v5
	v_cndmask_b32_e32 v163, v5, v85, vcc
	v_mul_f32_e32 v5, v7, v163
	v_mul_f32_e32 v7, v42, v163
	v_mul_f32_e32 v42, v43, v163
	v_mul_f32_e32 v43, v84, v163
	v_sub_f32_e32 v41, v41, v115
	v_sub_f32_e32 v39, v39, v115
	s_waitcnt lgkmcnt(0)
	v_fma_f32 v5, v5, v116, v120
	v_fmac_f32_e32 v123, v43, v119
	v_fma_f32 v7, v7, v117, v121
	v_fma_f32 v42, v42, v118, v122
	v_mul_f32_e32 v43, 0xbfb8aa3b, v5
	v_mul_f32_e32 v86, 0xbfb8aa3b, v123
	v_mul_f32_e32 v84, 0xbfb8aa3b, v7
	v_mul_f32_e32 v85, 0xbfb8aa3b, v42
	v_exp_f32_e32 v43, v43
	v_exp_f32_e32 v86, v86
	v_exp_f32_e32 v84, v84
	v_exp_f32_e32 v85, v85
	v_add_f32_e32 v43, 1.0, v43
	v_add_f32_e32 v86, 1.0, v86
	v_add_f32_e32 v84, 1.0, v84
	v_add_f32_e32 v85, 1.0, v85
	v_rcp_f32_e32 v43, v43
	v_rcp_f32_e32 v86, v86
	v_rcp_f32_e32 v84, v84
	v_rcp_f32_e32 v85, v85
	v_mul_f32_e32 v5, v5, v43
	v_mul_f32_e32 v43, v123, v86
	v_mul_f32_e32 v7, v7, v84
	v_mul_f32_e32 v42, v42, v85
	v_mul_f32_e32 v43, v43, v145
	v_mul_f32_e32 v5, v5, v137
	v_mul_f32_e32 v7, v7, v143
	v_mul_f32_e32 v84, v42, v144
	v_cvt_pk_bf16_f32 v42, v5, v7
	v_cvt_pk_bf16_f32 v43, v84, v43
	global_store_dwordx2 v[184:185], v[42:43], off
	ds_read_b128 v[84:87], v249 offset:1024
	ds_read_b128 v[116:119], v249 offset:5120
	v_sub_f32_e32 v38, v38, v115
	v_mul_f32_e32 v40, v40, v163
	v_mul_f32_e32 v41, v41, v163
	v_mul_f32_e32 v39, v39, v163
	v_mul_f32_e32 v38, v38, v163
	v_lshlrev_b32_e32 v5, 16, v18
	v_and_b32_e32 v7, 0xffff0000, v18
	v_lshlrev_b32_e32 v18, 16, v19
	v_and_b32_e32 v19, 0xffff0000, v19
	v_sub_f32_e32 v218, v16, v115
	v_sub_f32_e32 v219, v6, v115
	v_sub_f32_e32 v220, v17, v115
	v_sub_f32_e32 v221, v4, v115
	v_mul_f32_e32 v218, v218, v163
	v_mul_f32_e32 v219, v219, v163
	v_mul_f32_e32 v220, v220, v163
	v_mov_b64_e32 v[122:123], v[48:49]
	v_mov_b64_e32 v[136:137], v[30:31]
	v_mov_b64_e32 v[142:143], v[32:33]
	s_cmp_eq_u32 s12, 16
	v_mov_b32_e32 v4, v206
	v_mov_b32_e32 v6, v203
	v_mov_b32_e32 v114, v201
	v_mov_b64_e32 v[132:133], v[104:105]
	v_mov_b64_e32 v[16:17], v[102:103]
	v_mov_b64_e32 v[120:121], v[94:95]
	v_mov_b64_e32 v[144:145], v[78:79]
	v_mov_b32_e32 v124, v198
	v_mov_b32_e32 v125, v92
	s_waitcnt lgkmcnt(0)
	v_fma_f32 v40, v40, v84, v116
	v_fma_f32 v41, v41, v86, v118
	v_fmac_f32_e32 v119, v39, v87
	v_fma_f32 v38, v38, v85, v117
	v_mul_f32_e32 v39, 0xbfb8aa3b, v40
	v_mul_f32_e32 v43, 0xbfb8aa3b, v41
	v_mul_f32_e32 v84, 0xbfb8aa3b, v119
	v_mul_f32_e32 v42, 0xbfb8aa3b, v38
	v_exp_f32_e32 v39, v39
	v_exp_f32_e32 v43, v43
	v_exp_f32_e32 v84, v84
	v_exp_f32_e32 v42, v42
	v_add_f32_e32 v39, 1.0, v39
	v_add_f32_e32 v43, 1.0, v43
	v_add_f32_e32 v84, 1.0, v84
	v_add_f32_e32 v42, 1.0, v42
	v_rcp_f32_e32 v39, v39
	v_rcp_f32_e32 v43, v43
	v_rcp_f32_e32 v84, v84
	v_rcp_f32_e32 v42, v42
	v_mul_f32_e32 v39, v40, v39
	v_mul_f32_e32 v40, v41, v43
	v_mul_f32_e32 v41, v119, v84
	v_mul_f32_e32 v38, v38, v42
	v_mul_f32_e32 v19, v41, v19
	v_mul_f32_e32 v5, v39, v5
	v_mul_f32_e32 v7, v38, v7
	v_mul_f32_e32 v38, v40, v18
	v_cvt_pk_bf16_f32 v18, v5, v7
	v_cvt_pk_bf16_f32 v19, v38, v19
	global_store_dwordx2 v[184:185], v[18:19], off offset:512
	ds_read_b128 v[38:41], v249 offset:2048
	ds_read_b128 v[84:87], v249 offset:6144
	v_sub_f32_e32 v18, v21, v115
	v_sub_f32_e32 v21, v186, v115
	v_sub_f32_e32 v19, v20, v115
	v_sub_f32_e32 v20, v187, v115
	v_mul_f32_e32 v18, v18, v163
	v_mul_f32_e32 v21, v21, v163
	v_mul_f32_e32 v19, v19, v163
	v_mul_f32_e32 v20, v20, v163
	v_lshlrev_b32_e32 v5, 16, v14
	v_and_b32_e32 v7, 0xffff0000, v14
	v_lshlrev_b32_e32 v14, 16, v15
	v_and_b32_e32 v15, 0xffff0000, v15
	v_mul_f32_e32 v163, v221, v163
	v_mov_b64_e32 v[42:43], v[56:57]
	v_mov_b64_e32 v[118:119], v[46:47]
	v_mov_b32_e32 v186, v204
	v_mov_b32_e32 v187, v101
	v_mov_b32_e32 v116, v199
	v_mov_b32_e32 v115, v196
	v_mov_b32_e32 v117, v77
	s_waitcnt lgkmcnt(0)
	v_fma_f32 v18, v18, v38, v84
	v_fmac_f32_e32 v87, v21, v41
	v_fma_f32 v19, v19, v39, v85
	v_fma_f32 v20, v20, v40, v86
	v_mul_f32_e32 v21, 0xbfb8aa3b, v18
	v_mul_f32_e32 v40, 0xbfb8aa3b, v87
	v_mul_f32_e32 v38, 0xbfb8aa3b, v19
	v_mul_f32_e32 v39, 0xbfb8aa3b, v20
	v_exp_f32_e32 v21, v21
	v_exp_f32_e32 v40, v40
	v_exp_f32_e32 v38, v38
	v_exp_f32_e32 v39, v39
	v_add_f32_e32 v21, 1.0, v21
	v_add_f32_e32 v40, 1.0, v40
	v_add_f32_e32 v38, 1.0, v38
	v_add_f32_e32 v39, 1.0, v39
	v_rcp_f32_e32 v21, v21
	v_rcp_f32_e32 v40, v40
	v_rcp_f32_e32 v38, v38
	v_rcp_f32_e32 v39, v39
	v_mul_f32_e32 v18, v18, v21
	v_mul_f32_e32 v21, v87, v40
	v_mul_f32_e32 v19, v19, v38
	v_mul_f32_e32 v20, v20, v39
	v_mul_f32_e32 v15, v21, v15
	v_mul_f32_e32 v5, v18, v5
	v_mul_f32_e32 v7, v19, v7
	v_mul_f32_e32 v18, v20, v14
	v_cvt_pk_bf16_f32 v14, v5, v7
	v_cvt_pk_bf16_f32 v15, v18, v15
	global_store_dwordx2 v[184:185], v[14:15], off offset:1024
	ds_read_b128 v[208:211], v249 offset:3072
	ds_read_b128 v[212:215], v249 offset:7168
	v_lshlrev_b32_e32 v21, 16, v2
	v_mov_b64_e32 v[2:3], v[58:59]
	v_mov_b64_e32 v[14:15], v[52:53]
	v_mov_b64_e32 v[18:19], v[54:55]
	v_mov_b32_e32 v5, v200
	v_mov_b32_e32 v7, v93
	v_mov_b64_e32 v[38:39], v[112:113]
	v_mov_b64_e32 v[40:41], v[98:99]
	v_mov_b64_e32 v[84:85], v[110:111]
	v_mov_b64_e32 v[86:87], v[96:97]
	v_mov_b32_e32 v20, v202
	s_waitcnt lgkmcnt(0)
	v_fma_f32 v208, v218, v208, v212
	v_fma_f32 v209, v219, v209, v213
	v_fma_f32 v210, v220, v210, v214
	v_fmac_f32_e32 v215, v163, v211
	v_mul_f32_e32 v163, 0xbfb8aa3b, v208
	v_mul_f32_e32 v211, 0xbfb8aa3b, v209
	v_mul_f32_e32 v212, 0xbfb8aa3b, v210
	v_mul_f32_e32 v213, 0xbfb8aa3b, v215
	v_exp_f32_e32 v163, v163
	v_exp_f32_e32 v211, v211
	v_exp_f32_e32 v212, v212
	v_exp_f32_e32 v213, v213
	v_add_f32_e32 v163, 1.0, v163
	v_add_f32_e32 v211, 1.0, v211
	v_add_f32_e32 v212, 1.0, v212
	v_add_f32_e32 v213, 1.0, v213
	v_rcp_f32_e32 v163, v163
	v_rcp_f32_e32 v211, v211
	v_rcp_f32_e32 v212, v212
	v_rcp_f32_e32 v213, v213
	v_mul_f32_e32 v163, v208, v163
	v_mul_f32_e32 v208, v209, v211
	v_mul_f32_e32 v209, v210, v212
	v_mul_f32_e32 v210, v215, v213
	v_mul_f32_e32 v21, v163, v21
	v_mul_f32_e32 v163, v208, v165
	v_mul_f32_e32 v165, v209, v216
	v_mul_f32_e32 v209, v210, v217
	v_cvt_pk_bf16_f32 v208, v21, v163
	v_mov_b32_e32 v21, v100
	v_cvt_pk_bf16_f32 v209, v165, v209
	global_store_dwordx2 v[184:185], v[208:209], off offset:1536
	s_cbranch_scc1 .LBB0_404

.LBB0_665:
	ds_read_b128 v[108:111], v179
	ds_read_b128 v[136:139], v179 offset:1024
	ds_read_b128 v[140:143], v179 offset:2048
	ds_read_b128 v[144:147], v179 offset:3072
	s_add_i32 m0, s10, 0xc000
	s_add_i32 s8, s10, 0xe000
	s_add_i32 s9, s14, 0xfffc0080
	s_cmp_eq_u32 s13, 12
	s_cselect_b32 s48, s42, s36
	s_cselect_b32 s44, s43, s37
	v_lshl_add_u64 v[190:191], v[106:107], 0, s[14:15]
	ds_read_b128 v[160:163], v180
	ds_read_b128 v[164:167], v180 offset:1024
	ds_read_b128 v[168:171], v180 offset:2048
	ds_read_b128 v[172:175], v180 offset:3072
	ds_read_b128 v[182:185], v180 offset:4096
	ds_read_b128 v[186:189], v180 offset:5120
	ds_read_b128 v[194:197], v180 offset:6144
	ds_read_b128 v[198:201], v180 offset:7168
	global_load_lds_dwordx4 v[190:191], off
	v_lshl_add_u64 v[190:191], v[104:105], 0, s[14:15]
	s_mov_b32 m0, s8
	s_nop 0
	global_load_lds_dwordx4 v[190:191], off
	s_waitcnt lgkmcnt(8)
	s_barrier
	s_waitcnt lgkmcnt(0)
	s_setprio 1
	s_waitcnt lgkmcnt(0)
	v_mfma_f32_16x16x32_bf16 v[132:135], v[108:111], v[160:163], v[132:135]
	v_mfma_f32_16x16x32_bf16 v[128:131], v[140:143], v[160:163], v[128:131]
	v_mfma_f32_16x16x32_bf16 v[124:127], v[108:111], v[168:171], v[124:127]
	v_mfma_f32_16x16x32_bf16 v[120:123], v[140:143], v[168:171], v[120:123]
	v_mfma_f32_16x16x32_bf16 v[116:119], v[108:111], v[182:185], v[116:119]
	v_mfma_f32_16x16x32_bf16 v[112:115], v[140:143], v[182:185], v[112:115]
	v_mfma_f32_16x16x32_bf16 v[100:103], v[108:111], v[194:197], v[100:103]
	v_mfma_f32_16x16x32_bf16 v[96:99], v[140:143], v[194:197], v[96:99]
	v_mfma_f32_16x16x32_bf16 v[132:135], v[136:139], v[164:167], v[132:135]
	v_mfma_f32_16x16x32_bf16 v[128:131], v[144:147], v[164:167], v[128:131]
	v_mfma_f32_16x16x32_bf16 v[124:127], v[136:139], v[172:175], v[124:127]
	v_mfma_f32_16x16x32_bf16 v[120:123], v[144:147], v[172:175], v[120:123]
	v_mfma_f32_16x16x32_bf16 v[116:119], v[136:139], v[186:189], v[116:119]
	v_mfma_f32_16x16x32_bf16 v[112:115], v[144:147], v[186:189], v[112:115]
	v_mfma_f32_16x16x32_bf16 v[100:103], v[136:139], v[198:201], v[100:103]
	v_mfma_f32_16x16x32_bf16 v[96:99], v[144:147], v[198:201], v[96:99]
	s_setprio 0
	s_barrier
	s_cselect_b32 s8, 0, s9
	s_lshl_b32 s44, s44, 8
	s_ashr_i32 s45, s44, 31
	s_lshl_b64 s[46:47], s[44:45], 11
	s_add_u32 s9, s84, s46
	s_addc_u32 s45, s85, s47
	s_add_u32 s46, s9, s8
	s_addc_u32 s47, s45, 0
	s_add_i32 s9, s31, s3
	v_lshl_add_u64 v[190:191], s[46:47], 0, v[150:151]
	s_mov_b32 m0, s9
	ds_read_b128 v[208:211], v181
	ds_read_b128 v[212:215], v181 offset:1024
	ds_read_b128 v[216:219], v181 offset:2048
	ds_read_b128 v[220:223], v181 offset:3072
	global_load_lds_dwordx4 v[190:191], off
	v_lshl_add_u64 v[202:203], s[46:47], 0, v[154:155]
	s_add_i32 m0, s9, 0x2000
	s_nop 0
	global_load_lds_dwordx4 v[202:203], off
	s_barrier
	s_waitcnt lgkmcnt(0)
	s_setprio 1
	s_waitcnt lgkmcnt(0)
	v_mfma_f32_16x16x32_bf16 v[60:63], v[208:211], v[160:163], v[60:63]
	v_mfma_f32_16x16x32_bf16 v[56:59], v[216:219], v[160:163], v[56:59]
	v_mfma_f32_16x16x32_bf16 v[52:55], v[208:211], v[168:171], v[52:55]
	v_mfma_f32_16x16x32_bf16 v[48:51], v[216:219], v[168:171], v[48:51]
	v_mfma_f32_16x16x32_bf16 v[44:47], v[208:211], v[182:185], v[44:47]
	v_mfma_f32_16x16x32_bf16 v[40:43], v[216:219], v[182:185], v[40:43]
	v_mfma_f32_16x16x32_bf16 v[36:39], v[208:211], v[194:197], v[36:39]
	v_mfma_f32_16x16x32_bf16 v[32:35], v[216:219], v[194:197], v[32:35]
	v_mfma_f32_16x16x32_bf16 v[60:63], v[212:215], v[164:167], v[60:63]
	v_mfma_f32_16x16x32_bf16 v[56:59], v[220:223], v[164:167], v[56:59]
	v_mfma_f32_16x16x32_bf16 v[52:55], v[212:215], v[172:175], v[52:55]
	v_mfma_f32_16x16x32_bf16 v[48:51], v[220:223], v[172:175], v[48:51]
	v_mfma_f32_16x16x32_bf16 v[44:47], v[212:215], v[186:189], v[44:47]
	v_mfma_f32_16x16x32_bf16 v[40:43], v[220:223], v[186:189], v[40:43]
	v_mfma_f32_16x16x32_bf16 v[36:39], v[212:215], v[198:201], v[36:39]
	v_mfma_f32_16x16x32_bf16 v[32:35], v[220:223], v[198:201], v[32:35]
	s_setprio 0
	s_lshl_b32 s46, s48, 8
	s_ashr_i32 s47, s46, 31
	s_lshl_b64 s[48:49], s[46:47], 11
	s_add_u32 s9, s94, s48
	s_addc_u32 s45, s95, s49
	s_add_u32 s48, s9, s8
	s_addc_u32 s49, s45, 0
	s_mov_b32 m0, s10
	v_lshl_add_u64 v[224:225], s[48:49], 0, v[148:149]
	s_barrier
	ds_read_b128 v[160:163], v180 offset:16384
	ds_read_b128 v[164:167], v180 offset:17408
	ds_read_b128 v[168:171], v180 offset:18432
	ds_read_b128 v[172:175], v180 offset:19456
	ds_read_b128 v[182:185], v180 offset:20480
	ds_read_b128 v[186:189], v180 offset:21504
	ds_read_b128 v[194:197], v180 offset:22528
	ds_read_b128 v[198:201], v180 offset:23552
	global_load_lds_dwordx4 v[224:225], off
	v_lshl_add_u64 v[226:227], s[48:49], 0, v[152:153]
	s_mov_b32 m0, s11
	s_nop 0
	global_load_lds_dwordx4 v[226:227], off
	s_barrier
	s_waitcnt lgkmcnt(0)
	s_setprio 1
	s_waitcnt lgkmcnt(0)
	v_mfma_f32_16x16x32_bf16 v[92:95], v[108:111], v[160:163], v[92:95]
	v_mfma_f32_16x16x32_bf16 v[88:91], v[140:143], v[160:163], v[88:91]
	v_mfma_f32_16x16x32_bf16 v[84:87], v[108:111], v[168:171], v[84:87]
	v_mfma_f32_16x16x32_bf16 v[80:83], v[140:143], v[168:171], v[80:83]
	v_mfma_f32_16x16x32_bf16 v[76:79], v[108:111], v[182:185], v[76:79]
	v_mfma_f32_16x16x32_bf16 v[72:75], v[140:143], v[182:185], v[72:75]
	v_mfma_f32_16x16x32_bf16 v[68:71], v[108:111], v[194:197], v[68:71]
	v_mfma_f32_16x16x32_bf16 v[64:67], v[140:143], v[194:197], v[64:67]
	v_mfma_f32_16x16x32_bf16 v[92:95], v[136:139], v[164:167], v[92:95]
	v_mfma_f32_16x16x32_bf16 v[88:91], v[144:147], v[164:167], v[88:91]
	v_mfma_f32_16x16x32_bf16 v[84:87], v[136:139], v[172:175], v[84:87]
	v_mfma_f32_16x16x32_bf16 v[80:83], v[144:147], v[172:175], v[80:83]
	v_mfma_f32_16x16x32_bf16 v[76:79], v[136:139], v[186:189], v[76:79]
	v_mfma_f32_16x16x32_bf16 v[72:75], v[144:147], v[186:189], v[72:75]
	v_mfma_f32_16x16x32_bf16 v[68:71], v[136:139], v[198:201], v[68:71]
	v_mfma_f32_16x16x32_bf16 v[64:67], v[144:147], v[198:201], v[64:67]
	s_setprio 0
	s_barrier
	s_bitset1_b32 s44, 7
	s_ashr_i32 s45, s44, 31
	s_lshl_b64 s[44:45], s[44:45], 11
	s_add_u32 s9, s84, s44
	s_addc_u32 s45, s85, s45
	s_add_u32 s44, s9, s8
	s_addc_u32 s45, s45, 0
	s_add_i32 s9, s33, s3
	v_lshl_add_u64 v[228:229], s[44:45], 0, v[150:151]
	s_mov_b32 m0, s9
	v_lshl_add_u64 v[230:231], s[44:45], 0, v[154:155]
	global_load_lds_dwordx4 v[228:229], off
	s_add_i32 m0, s9, 0x2000
	s_nop 0
	global_load_lds_dwordx4 v[230:231], off
	s_waitcnt vmcnt(6)
	s_barrier
	s_setprio 1
	v_mfma_f32_16x16x32_bf16 v[28:31], v[208:211], v[160:163], v[28:31]
	v_mfma_f32_16x16x32_bf16 v[24:27], v[216:219], v[160:163], v[24:27]
	v_mfma_f32_16x16x32_bf16 v[20:23], v[208:211], v[168:171], v[20:23]
	v_mfma_f32_16x16x32_bf16 v[16:19], v[216:219], v[168:171], v[16:19]
	v_mfma_f32_16x16x32_bf16 v[12:15], v[208:211], v[182:185], v[12:15]
	v_mfma_f32_16x16x32_bf16 v[8:11], v[216:219], v[182:185], v[8:11]
	v_mfma_f32_16x16x32_bf16 v[4:7], v[208:211], v[194:197], v[4:7]
	v_mfma_f32_16x16x32_bf16 v[0:3], v[216:219], v[194:197], v[0:3]
	v_mfma_f32_16x16x32_bf16 v[28:31], v[212:215], v[164:167], v[28:31]
	v_mfma_f32_16x16x32_bf16 v[24:27], v[220:223], v[164:167], v[24:27]
	v_mfma_f32_16x16x32_bf16 v[20:23], v[212:215], v[172:175], v[20:23]
	v_mfma_f32_16x16x32_bf16 v[16:19], v[220:223], v[172:175], v[16:19]
	v_mfma_f32_16x16x32_bf16 v[12:15], v[212:215], v[186:189], v[12:15]
	v_mfma_f32_16x16x32_bf16 v[8:11], v[220:223], v[186:189], v[8:11]
	v_mfma_f32_16x16x32_bf16 v[4:7], v[212:215], v[198:201], v[4:7]
	v_mfma_f32_16x16x32_bf16 v[0:3], v[220:223], v[198:201], v[0:3]
	s_setprio 0
	s_add_i32 s9, 0, 0x18000
	v_add_u32_e32 v144, s9, v177
	s_barrier
	ds_read_b128 v[108:111], v144
	ds_read_b128 v[136:139], v144 offset:1024
	ds_read_b128 v[140:143], v144 offset:2048
	ds_read_b128 v[144:147], v144 offset:3072
	s_or_b32 s44, s46, 0x80
	s_ashr_i32 s45, s44, 31
	s_lshl_b64 s[44:45], s[44:45], 11
	s_add_u32 s44, s94, s44
	s_addc_u32 s45, s95, s45
	s_add_u32 s44, s44, s8
	s_addc_u32 s45, s45, 0
	s_mov_b32 m0, s22
	v_lshl_add_u64 v[208:209], s[44:45], 0, v[148:149]
	ds_read_b128 v[160:163], v180 offset:32768
	ds_read_b128 v[164:167], v180 offset:33792
	ds_read_b128 v[168:171], v180 offset:34816
	ds_read_b128 v[172:175], v180 offset:35840
	ds_read_b128 v[182:185], v180 offset:36864
	ds_read_b128 v[186:189], v180 offset:37888
	ds_read_b128 v[194:197], v180 offset:38912
	ds_read_b128 v[198:201], v180 offset:39936
	global_load_lds_dwordx4 v[208:209], off
	v_lshl_add_u64 v[208:209], s[44:45], 0, v[152:153]
	s_mov_b32 m0, s23
	s_nop 0
	global_load_lds_dwordx4 v[208:209], off
	s_waitcnt lgkmcnt(8)
	s_barrier
	s_waitcnt lgkmcnt(0)
	s_setprio 1
	s_waitcnt lgkmcnt(0)
	v_mfma_f32_16x16x32_bf16 v[132:135], v[108:111], v[160:163], v[132:135]
	v_mfma_f32_16x16x32_bf16 v[128:131], v[140:143], v[160:163], v[128:131]
	v_mfma_f32_16x16x32_bf16 v[124:127], v[108:111], v[168:171], v[124:127]
	v_mfma_f32_16x16x32_bf16 v[120:123], v[140:143], v[168:171], v[120:123]
	v_mfma_f32_16x16x32_bf16 v[116:119], v[108:111], v[182:185], v[116:119]
	v_mfma_f32_16x16x32_bf16 v[112:115], v[140:143], v[182:185], v[112:115]
	v_mfma_f32_16x16x32_bf16 v[100:103], v[108:111], v[194:197], v[100:103]
	v_mfma_f32_16x16x32_bf16 v[96:99], v[140:143], v[194:197], v[96:99]
	v_mfma_f32_16x16x32_bf16 v[132:135], v[136:139], v[164:167], v[132:135]
	v_mfma_f32_16x16x32_bf16 v[128:131], v[144:147], v[164:167], v[128:131]
	v_mfma_f32_16x16x32_bf16 v[124:127], v[136:139], v[172:175], v[124:127]
	v_mfma_f32_16x16x32_bf16 v[120:123], v[144:147], v[172:175], v[120:123]
	v_mfma_f32_16x16x32_bf16 v[116:119], v[136:139], v[186:189], v[116:119]
	v_mfma_f32_16x16x32_bf16 v[112:115], v[144:147], v[186:189], v[112:115]
	v_mfma_f32_16x16x32_bf16 v[100:103], v[136:139], v[198:201], v[100:103]
	v_mfma_f32_16x16x32_bf16 v[96:99], v[144:147], v[198:201], v[96:99]
	s_setprio 0
	s_barrier
	s_add_i32 s8, 0, 0x1c000
	s_add_i32 s9, s9, s3
	v_add_u32_e32 v204, s8, v177
	v_lshl_add_u64 v[190:191], v[190:191], 0, s[0:1]
	s_mov_b32 m0, s9
	ds_read_b128 v[208:211], v204
	ds_read_b128 v[212:215], v204 offset:1024
	ds_read_b128 v[216:219], v204 offset:2048
	ds_read_b128 v[220:223], v204 offset:3072
	global_load_lds_dwordx4 v[190:191], off
	v_lshl_add_u64 v[190:191], v[202:203], 0, s[0:1]
	s_add_i32 m0, s9, 0x2000
	s_nop 0
	global_load_lds_dwordx4 v[190:191], off
	s_barrier
	s_waitcnt lgkmcnt(0)
	s_setprio 1
	s_waitcnt lgkmcnt(0)
	v_mfma_f32_16x16x32_bf16 v[60:63], v[208:211], v[160:163], v[60:63]
	v_mfma_f32_16x16x32_bf16 v[56:59], v[216:219], v[160:163], v[56:59]
	v_mfma_f32_16x16x32_bf16 v[52:55], v[208:211], v[168:171], v[52:55]
	v_mfma_f32_16x16x32_bf16 v[48:51], v[216:219], v[168:171], v[48:51]
	v_mfma_f32_16x16x32_bf16 v[44:47], v[208:211], v[182:185], v[44:47]
	v_mfma_f32_16x16x32_bf16 v[40:43], v[216:219], v[182:185], v[40:43]
	v_mfma_f32_16x16x32_bf16 v[36:39], v[208:211], v[194:197], v[36:39]
	v_mfma_f32_16x16x32_bf16 v[32:35], v[216:219], v[194:197], v[32:35]
	v_mfma_f32_16x16x32_bf16 v[60:63], v[212:215], v[164:167], v[60:63]
	v_mfma_f32_16x16x32_bf16 v[56:59], v[220:223], v[164:167], v[56:59]
	v_mfma_f32_16x16x32_bf16 v[52:55], v[212:215], v[172:175], v[52:55]
	v_mfma_f32_16x16x32_bf16 v[48:51], v[220:223], v[172:175], v[48:51]
	v_mfma_f32_16x16x32_bf16 v[44:47], v[212:215], v[186:189], v[44:47]
	v_mfma_f32_16x16x32_bf16 v[40:43], v[220:223], v[186:189], v[40:43]
	v_mfma_f32_16x16x32_bf16 v[36:39], v[212:215], v[198:201], v[36:39]
	v_mfma_f32_16x16x32_bf16 v[32:35], v[220:223], v[198:201], v[32:35]
	s_setprio 0
	s_mov_b32 m0, s25
	v_lshl_add_u64 v[190:191], v[224:225], 0, s[0:1]
	s_barrier
	ds_read_b128 v[160:163], v180 offset:49152
	ds_read_b128 v[164:167], v180 offset:50176
	ds_read_b128 v[168:171], v180 offset:51200
	ds_read_b128 v[172:175], v180 offset:52224
	ds_read_b128 v[182:185], v180 offset:53248
	ds_read_b128 v[186:189], v180 offset:54272
	ds_read_b128 v[194:197], v180 offset:55296
	ds_read_b128 v[198:201], v180 offset:56320
	global_load_lds_dwordx4 v[190:191], off
	v_lshl_add_u64 v[190:191], v[226:227], 0, s[0:1]
	s_mov_b32 m0, s30
	s_nop 0
	global_load_lds_dwordx4 v[190:191], off
	s_barrier
	s_waitcnt lgkmcnt(0)
	s_setprio 1
	s_waitcnt lgkmcnt(0)
	v_mfma_f32_16x16x32_bf16 v[92:95], v[108:111], v[160:163], v[92:95]
	v_mfma_f32_16x16x32_bf16 v[88:91], v[140:143], v[160:163], v[88:91]
	v_mfma_f32_16x16x32_bf16 v[84:87], v[108:111], v[168:171], v[84:87]
	v_mfma_f32_16x16x32_bf16 v[80:83], v[140:143], v[168:171], v[80:83]
	v_mfma_f32_16x16x32_bf16 v[76:79], v[108:111], v[182:185], v[76:79]
	v_mfma_f32_16x16x32_bf16 v[72:75], v[140:143], v[182:185], v[72:75]
	v_mfma_f32_16x16x32_bf16 v[68:71], v[108:111], v[194:197], v[68:71]
	v_mfma_f32_16x16x32_bf16 v[64:67], v[140:143], v[194:197], v[64:67]
	v_mfma_f32_16x16x32_bf16 v[92:95], v[136:139], v[164:167], v[92:95]
	v_mfma_f32_16x16x32_bf16 v[88:91], v[144:147], v[164:167], v[88:91]
	v_mfma_f32_16x16x32_bf16 v[84:87], v[136:139], v[172:175], v[84:87]
	v_mfma_f32_16x16x32_bf16 v[80:83], v[144:147], v[172:175], v[80:83]
	v_mfma_f32_16x16x32_bf16 v[76:79], v[136:139], v[186:189], v[76:79]
	v_mfma_f32_16x16x32_bf16 v[72:75], v[144:147], v[186:189], v[72:75]
	v_mfma_f32_16x16x32_bf16 v[68:71], v[136:139], v[198:201], v[68:71]
	v_mfma_f32_16x16x32_bf16 v[64:67], v[144:147], v[198:201], v[64:67]
	s_setprio 0
	s_barrier
	s_add_i32 s8, s8, s3
	v_lshl_add_u64 v[108:109], v[228:229], 0, s[0:1]
	s_mov_b32 m0, s8
	s_nop 0
	global_load_lds_dwordx4 v[108:109], off
	v_lshl_add_u64 v[108:109], v[230:231], 0, s[0:1]
	s_add_i32 m0, s8, 0x2000
	s_nop 0
	global_load_lds_dwordx4 v[108:109], off
	s_waitcnt vmcnt(6)
	s_barrier
	s_setprio 1
	v_mfma_f32_16x16x32_bf16 v[28:31], v[208:211], v[160:163], v[28:31]
	v_mfma_f32_16x16x32_bf16 v[24:27], v[216:219], v[160:163], v[24:27]
	v_mfma_f32_16x16x32_bf16 v[20:23], v[208:211], v[168:171], v[20:23]
	v_mfma_f32_16x16x32_bf16 v[16:19], v[216:219], v[168:171], v[16:19]
	v_mfma_f32_16x16x32_bf16 v[12:15], v[208:211], v[182:185], v[12:15]
	v_mfma_f32_16x16x32_bf16 v[8:11], v[216:219], v[182:185], v[8:11]
	v_mfma_f32_16x16x32_bf16 v[4:7], v[208:211], v[194:197], v[4:7]
	v_mfma_f32_16x16x32_bf16 v[0:3], v[216:219], v[194:197], v[0:3]
	v_mfma_f32_16x16x32_bf16 v[28:31], v[212:215], v[164:167], v[28:31]
	v_mfma_f32_16x16x32_bf16 v[24:27], v[220:223], v[164:167], v[24:27]
	v_mfma_f32_16x16x32_bf16 v[20:23], v[212:215], v[172:175], v[20:23]
	v_mfma_f32_16x16x32_bf16 v[16:19], v[220:223], v[172:175], v[16:19]
	v_mfma_f32_16x16x32_bf16 v[12:15], v[212:215], v[186:189], v[12:15]
	v_mfma_f32_16x16x32_bf16 v[8:11], v[220:223], v[186:189], v[8:11]
	v_mfma_f32_16x16x32_bf16 v[4:7], v[212:215], v[198:201], v[4:7]
	v_mfma_f32_16x16x32_bf16 v[0:3], v[220:223], v[198:201], v[0:3]
	s_setprio 0
	s_add_i32 s13, s13, 2
	s_add_u32 s14, s14, 0x100
	s_addc_u32 s15, s15, 0
	s_cmp_gt_u32 s13, 13
	s_barrier
	s_cbranch_scc0 .LBB0_665
	v_lshl_or_b32 v250, s37, 8, v178
	v_ashrrev_i32_e32 v251, 31, v250
	v_add_u32_e32 v252, s12, v176
	v_ashrrev_i32_e32 v253, 31, v252
	v_readlane_b32 s54, v241, 44
	v_readlane_b32 s55, v241, 45
	s_mov_b32 s36, s34
	s_mov_b32 s37, s35
	v_lshlrev_b64 v[246:247], 1, v[250:251]
	v_lshlrev_b64 v[248:249], 11, v[252:253]
	v_lshl_add_u64 v[246:247], v[246:247], 0, v[248:249]
	v_lshl_add_u64 v[254:255], v[250:251], 2, s[54:55]
	global_load_dwordx4 v[108:111], v[254:255], off
	global_load_dwordx4 v[104:107], v[254:255], off offset:16
	global_load_dwordx4 v[236:239], v[254:255], off offset:512
	global_load_dwordx4 v[242:245], v[254:255], off offset:528
	v_lshl_add_u64 v[248:249], v[246:247], 0, s[40:41]
	v_lshl_add_u64 v[246:247], v[246:247], 0, s[94:95]
	global_load_dwordx4 v[136:139], v[246:247], off
	global_load_dwordx4 v[140:143], v[248:249], off
	s_mov_b64 s[100:101], 0x8000
	v_lshl_add_u64 v[250:251], v[246:247], 0, s[100:101]
	v_lshl_add_u64 v[252:253], v[248:249], 0, s[100:101]
	global_load_dwordx4 v[144:147], v[250:251], off
	global_load_dwordx4 v[160:163], v[252:253], off
	s_mov_b64 s[100:101], 0x10000
	v_lshl_add_u64 v[250:251], v[246:247], 0, s[100:101]
	v_lshl_add_u64 v[252:253], v[248:249], 0, s[100:101]
	global_load_dwordx4 v[164:167], v[250:251], off
	global_load_dwordx4 v[168:171], v[252:253], off
	s_mov_b64 s[100:101], 0x18000
	v_lshl_add_u64 v[250:251], v[246:247], 0, s[100:101]
	v_lshl_add_u64 v[252:253], v[248:249], 0, s[100:101]
	global_load_dwordx4 v[172:175], v[250:251], off
	global_load_dwordx4 v[182:185], v[252:253], off
	s_mov_b64 s[100:101], 0x40000
	v_lshl_add_u64 v[250:251], v[246:247], 0, s[100:101]
	v_lshl_add_u64 v[252:253], v[248:249], 0, s[100:101]
	global_load_dwordx4 v[186:189], v[250:251], off
	global_load_dwordx4 v[194:197], v[252:253], off
	s_mov_b64 s[100:101], 0x48000
	v_lshl_add_u64 v[250:251], v[246:247], 0, s[100:101]
	v_lshl_add_u64 v[252:253], v[248:249], 0, s[100:101]
	global_load_dwordx4 v[198:201], v[250:251], off
	global_load_dwordx4 v[208:211], v[252:253], off
	s_mov_b64 s[100:101], 0x50000
	v_lshl_add_u64 v[250:251], v[246:247], 0, s[100:101]
	v_lshl_add_u64 v[252:253], v[248:249], 0, s[100:101]
	global_load_dwordx4 v[212:215], v[250:251], off
	global_load_dwordx4 v[216:219], v[252:253], off
	s_mov_b64 s[100:101], 0x58000
	v_lshl_add_u64 v[250:251], v[246:247], 0, s[100:101]
	v_lshl_add_u64 v[252:253], v[248:249], 0, s[100:101]
	global_load_dwordx4 v[220:223], v[250:251], off
	global_load_dwordx4 v[232:235], v[252:253], off
	s_waitcnt vmcnt(14)
	v_pk_add_f32 v[132:133], v[132:133], v[108:109]
	v_pk_add_f32 v[134:135], v[134:135], v[110:111]
	v_pk_add_f32 v[128:129], v[128:129], v[104:105]
	v_pk_add_f32 v[130:131], v[130:131], v[106:107]
	v_mul_f32_e32 v132, 0xbfb8aa3b, v132
	v_mul_f32_e32 v133, 0xbfb8aa3b, v133
	v_mul_f32_e32 v134, 0xbfb8aa3b, v134
	v_mul_f32_e32 v135, 0xbfb8aa3b, v135
	v_mul_f32_e32 v128, 0xbfb8aa3b, v128
	v_mul_f32_e32 v129, 0xbfb8aa3b, v129
	v_mul_f32_e32 v130, 0xbfb8aa3b, v130
	v_mul_f32_e32 v131, 0xbfb8aa3b, v131
	v_exp_f32_e32 v132, v132
	v_exp_f32_e32 v133, v133
	v_exp_f32_e32 v134, v134
	v_exp_f32_e32 v135, v135
	v_exp_f32_e32 v128, v128
	v_exp_f32_e32 v129, v129
	v_exp_f32_e32 v130, v130
	v_exp_f32_e32 v131, v131
	v_add_f32_e32 v132, 1.0, v132
	v_add_f32_e32 v133, 1.0, v133
	v_add_f32_e32 v134, 1.0, v134
	v_add_f32_e32 v135, 1.0, v135
	v_add_f32_e32 v128, 1.0, v128
	v_add_f32_e32 v129, 1.0, v129
	v_add_f32_e32 v130, 1.0, v130
	v_add_f32_e32 v131, 1.0, v131
	v_rcp_f32_e32 v132, v132
	v_rcp_f32_e32 v133, v133
	v_rcp_f32_e32 v134, v134
	v_rcp_f32_e32 v135, v135
	v_rcp_f32_e32 v128, v128
	v_rcp_f32_e32 v129, v129
	v_rcp_f32_e32 v130, v130
	v_rcp_f32_e32 v131, v131
	v_lshlrev_b32_e32 v254, 16, v136
	v_and_b32_e32 v255, 0xffff0000, v136
	v_mul_f32_e32 v132, v132, v254
	v_mul_f32_e32 v133, v133, v255
	v_lshlrev_b32_e32 v254, 16, v140
	v_and_b32_e32 v255, 0xffff0000, v140
	v_mul_f32_e32 v132, v132, v254
	v_mul_f32_e32 v133, v133, v255
	v_cvt_pk_bf16_f32 v140, v132, v133
	v_lshlrev_b32_e32 v254, 16, v137
	v_and_b32_e32 v255, 0xffff0000, v137
	v_mul_f32_e32 v134, v134, v254
	v_mul_f32_e32 v135, v135, v255
	v_lshlrev_b32_e32 v254, 16, v141
	v_and_b32_e32 v255, 0xffff0000, v141
	v_mul_f32_e32 v134, v134, v254
	v_mul_f32_e32 v135, v135, v255
	v_cvt_pk_bf16_f32 v141, v134, v135
	v_lshlrev_b32_e32 v254, 16, v138
	v_and_b32_e32 v255, 0xffff0000, v138
	v_mul_f32_e32 v128, v128, v254
	v_mul_f32_e32 v129, v129, v255
	v_lshlrev_b32_e32 v254, 16, v142
	v_and_b32_e32 v255, 0xffff0000, v142
	v_mul_f32_e32 v128, v128, v254
	v_mul_f32_e32 v129, v129, v255
	v_cvt_pk_bf16_f32 v142, v128, v129
	v_lshlrev_b32_e32 v254, 16, v139
	v_and_b32_e32 v255, 0xffff0000, v139
	v_mul_f32_e32 v130, v130, v254
	v_mul_f32_e32 v131, v131, v255
	v_lshlrev_b32_e32 v254, 16, v143
	v_and_b32_e32 v255, 0xffff0000, v143
	v_mul_f32_e32 v130, v130, v254
	v_mul_f32_e32 v131, v131, v255
	v_cvt_pk_bf16_f32 v143, v130, v131
	global_store_dwordx4 v[248:249], v[140:143], off
	global_load_dwordx4 v[136:139], v[246:247], off offset:256
	global_load_dwordx4 v[140:143], v[248:249], off offset:256
	s_waitcnt vmcnt(15)
	v_pk_add_f32 v[124:125], v[124:125], v[108:109]
	v_pk_add_f32 v[126:127], v[126:127], v[110:111]
	v_pk_add_f32 v[120:121], v[120:121], v[104:105]
	v_pk_add_f32 v[122:123], v[122:123], v[106:107]
	v_mul_f32_e32 v124, 0xbfb8aa3b, v124
	v_mul_f32_e32 v125, 0xbfb8aa3b, v125
	v_mul_f32_e32 v126, 0xbfb8aa3b, v126
	v_mul_f32_e32 v127, 0xbfb8aa3b, v127
	v_mul_f32_e32 v120, 0xbfb8aa3b, v120
	v_mul_f32_e32 v121, 0xbfb8aa3b, v121
	v_mul_f32_e32 v122, 0xbfb8aa3b, v122
	v_mul_f32_e32 v123, 0xbfb8aa3b, v123
	v_exp_f32_e32 v124, v124
	v_exp_f32_e32 v125, v125
	v_exp_f32_e32 v126, v126
	v_exp_f32_e32 v127, v127
	v_exp_f32_e32 v120, v120
	v_exp_f32_e32 v121, v121
	v_exp_f32_e32 v122, v122
	v_exp_f32_e32 v123, v123
	v_add_f32_e32 v124, 1.0, v124
	v_add_f32_e32 v125, 1.0, v125
	v_add_f32_e32 v126, 1.0, v126
	v_add_f32_e32 v127, 1.0, v127
	v_add_f32_e32 v120, 1.0, v120
	v_add_f32_e32 v121, 1.0, v121
	v_add_f32_e32 v122, 1.0, v122
	v_add_f32_e32 v123, 1.0, v123
	v_rcp_f32_e32 v124, v124
	v_rcp_f32_e32 v125, v125
	v_rcp_f32_e32 v126, v126
	v_rcp_f32_e32 v127, v127
	v_rcp_f32_e32 v120, v120
	v_rcp_f32_e32 v121, v121
	v_rcp_f32_e32 v122, v122
	v_rcp_f32_e32 v123, v123
	v_lshlrev_b32_e32 v254, 16, v144
	v_and_b32_e32 v255, 0xffff0000, v144
	v_mul_f32_e32 v124, v124, v254
	v_mul_f32_e32 v125, v125, v255
	v_lshlrev_b32_e32 v254, 16, v160
	v_and_b32_e32 v255, 0xffff0000, v160
	v_mul_f32_e32 v124, v124, v254
	v_mul_f32_e32 v125, v125, v255
	v_cvt_pk_bf16_f32 v160, v124, v125
	v_lshlrev_b32_e32 v254, 16, v145
	v_and_b32_e32 v255, 0xffff0000, v145
	v_mul_f32_e32 v126, v126, v254
	v_mul_f32_e32 v127, v127, v255
	v_lshlrev_b32_e32 v254, 16, v161
	v_and_b32_e32 v255, 0xffff0000, v161
	v_mul_f32_e32 v126, v126, v254
	v_mul_f32_e32 v127, v127, v255
	v_cvt_pk_bf16_f32 v161, v126, v127
	v_lshlrev_b32_e32 v254, 16, v146
	v_and_b32_e32 v255, 0xffff0000, v146
	v_mul_f32_e32 v120, v120, v254
	v_mul_f32_e32 v121, v121, v255
	v_lshlrev_b32_e32 v254, 16, v162
	v_and_b32_e32 v255, 0xffff0000, v162
	v_mul_f32_e32 v120, v120, v254
	v_mul_f32_e32 v121, v121, v255
	v_cvt_pk_bf16_f32 v162, v120, v121
	v_lshlrev_b32_e32 v254, 16, v147
	v_and_b32_e32 v255, 0xffff0000, v147
	v_mul_f32_e32 v122, v122, v254
	v_mul_f32_e32 v123, v123, v255
	v_lshlrev_b32_e32 v254, 16, v163
	v_and_b32_e32 v255, 0xffff0000, v163
	v_mul_f32_e32 v122, v122, v254
	v_mul_f32_e32 v123, v123, v255
	v_cvt_pk_bf16_f32 v163, v122, v123
	s_mov_b64 s[100:101], 0x8000
	v_lshl_add_u64 v[190:191], v[248:249], 0, s[100:101]
	global_store_dwordx4 v[190:191], v[160:163], off
	s_mov_b64 s[100:101], 0x8000
	v_lshl_add_u64 v[250:251], v[246:247], 0, s[100:101]
	v_lshl_add_u64 v[252:253], v[248:249], 0, s[100:101]
	global_load_dwordx4 v[144:147], v[250:251], off offset:256
	global_load_dwordx4 v[160:163], v[252:253], off offset:256
	s_waitcnt vmcnt(16)
	v_pk_add_f32 v[116:117], v[116:117], v[108:109]
	v_pk_add_f32 v[118:119], v[118:119], v[110:111]
	v_pk_add_f32 v[112:113], v[112:113], v[104:105]
	v_pk_add_f32 v[114:115], v[114:115], v[106:107]
	v_mul_f32_e32 v116, 0xbfb8aa3b, v116
	v_mul_f32_e32 v117, 0xbfb8aa3b, v117
	v_mul_f32_e32 v118, 0xbfb8aa3b, v118
	v_mul_f32_e32 v119, 0xbfb8aa3b, v119
	v_mul_f32_e32 v112, 0xbfb8aa3b, v112
	v_mul_f32_e32 v113, 0xbfb8aa3b, v113
	v_mul_f32_e32 v114, 0xbfb8aa3b, v114
	v_mul_f32_e32 v115, 0xbfb8aa3b, v115
	v_exp_f32_e32 v116, v116
	v_exp_f32_e32 v117, v117
	v_exp_f32_e32 v118, v118
	v_exp_f32_e32 v119, v119
	v_exp_f32_e32 v112, v112
	v_exp_f32_e32 v113, v113
	v_exp_f32_e32 v114, v114
	v_exp_f32_e32 v115, v115
	v_add_f32_e32 v116, 1.0, v116
	v_add_f32_e32 v117, 1.0, v117
	v_add_f32_e32 v118, 1.0, v118
	v_add_f32_e32 v119, 1.0, v119
	v_add_f32_e32 v112, 1.0, v112
	v_add_f32_e32 v113, 1.0, v113
	v_add_f32_e32 v114, 1.0, v114
	v_add_f32_e32 v115, 1.0, v115
	v_rcp_f32_e32 v116, v116
	v_rcp_f32_e32 v117, v117
	v_rcp_f32_e32 v118, v118
	v_rcp_f32_e32 v119, v119
	v_rcp_f32_e32 v112, v112
	v_rcp_f32_e32 v113, v113
	v_rcp_f32_e32 v114, v114
	v_rcp_f32_e32 v115, v115
	v_lshlrev_b32_e32 v254, 16, v164
	v_and_b32_e32 v255, 0xffff0000, v164
	v_mul_f32_e32 v116, v116, v254
	v_mul_f32_e32 v117, v117, v255
	v_lshlrev_b32_e32 v254, 16, v168
	v_and_b32_e32 v255, 0xffff0000, v168
	v_mul_f32_e32 v116, v116, v254
	v_mul_f32_e32 v117, v117, v255
	v_cvt_pk_bf16_f32 v168, v116, v117
	v_lshlrev_b32_e32 v254, 16, v165
	v_and_b32_e32 v255, 0xffff0000, v165
	v_mul_f32_e32 v118, v118, v254
	v_mul_f32_e32 v119, v119, v255
	v_lshlrev_b32_e32 v254, 16, v169
	v_and_b32_e32 v255, 0xffff0000, v169
	v_mul_f32_e32 v118, v118, v254
	v_mul_f32_e32 v119, v119, v255
	v_cvt_pk_bf16_f32 v169, v118, v119
	v_lshlrev_b32_e32 v254, 16, v166
	v_and_b32_e32 v255, 0xffff0000, v166
	v_mul_f32_e32 v112, v112, v254
	v_mul_f32_e32 v113, v113, v255
	v_lshlrev_b32_e32 v254, 16, v170
	v_and_b32_e32 v255, 0xffff0000, v170
	v_mul_f32_e32 v112, v112, v254
	v_mul_f32_e32 v113, v113, v255
	v_cvt_pk_bf16_f32 v170, v112, v113
	v_lshlrev_b32_e32 v254, 16, v167
	v_and_b32_e32 v255, 0xffff0000, v167
	v_mul_f32_e32 v114, v114, v254
	v_mul_f32_e32 v115, v115, v255
	v_lshlrev_b32_e32 v254, 16, v171
	v_and_b32_e32 v255, 0xffff0000, v171
	v_mul_f32_e32 v114, v114, v254
	v_mul_f32_e32 v115, v115, v255
	v_cvt_pk_bf16_f32 v171, v114, v115
	s_mov_b64 s[100:101], 0x10000
	v_lshl_add_u64 v[190:191], v[248:249], 0, s[100:101]
	global_store_dwordx4 v[190:191], v[168:171], off
	s_mov_b64 s[100:101], 0x10000
	v_lshl_add_u64 v[250:251], v[246:247], 0, s[100:101]
	v_lshl_add_u64 v[252:253], v[248:249], 0, s[100:101]
	global_load_dwordx4 v[164:167], v[250:251], off offset:256
	global_load_dwordx4 v[168:171], v[252:253], off offset:256
	s_waitcnt vmcnt(17)
	v_pk_add_f32 v[100:101], v[100:101], v[108:109]
	v_pk_add_f32 v[102:103], v[102:103], v[110:111]
	v_pk_add_f32 v[96:97], v[96:97], v[104:105]
	v_pk_add_f32 v[98:99], v[98:99], v[106:107]
	v_mul_f32_e32 v100, 0xbfb8aa3b, v100
	v_mul_f32_e32 v101, 0xbfb8aa3b, v101
	v_mul_f32_e32 v102, 0xbfb8aa3b, v102
	v_mul_f32_e32 v103, 0xbfb8aa3b, v103
	v_mul_f32_e32 v96, 0xbfb8aa3b, v96
	v_mul_f32_e32 v97, 0xbfb8aa3b, v97
	v_mul_f32_e32 v98, 0xbfb8aa3b, v98
	v_mul_f32_e32 v99, 0xbfb8aa3b, v99
	v_exp_f32_e32 v100, v100
	v_exp_f32_e32 v101, v101
	v_exp_f32_e32 v102, v102
	v_exp_f32_e32 v103, v103
	v_exp_f32_e32 v96, v96
	v_exp_f32_e32 v97, v97
	v_exp_f32_e32 v98, v98
	v_exp_f32_e32 v99, v99
	v_add_f32_e32 v100, 1.0, v100
	v_add_f32_e32 v101, 1.0, v101
	v_add_f32_e32 v102, 1.0, v102
	v_add_f32_e32 v103, 1.0, v103
	v_add_f32_e32 v96, 1.0, v96
	v_add_f32_e32 v97, 1.0, v97
	v_add_f32_e32 v98, 1.0, v98
	v_add_f32_e32 v99, 1.0, v99
	v_rcp_f32_e32 v100, v100
	v_rcp_f32_e32 v101, v101
	v_rcp_f32_e32 v102, v102
	v_rcp_f32_e32 v103, v103
	v_rcp_f32_e32 v96, v96
	v_rcp_f32_e32 v97, v97
	v_rcp_f32_e32 v98, v98
	v_rcp_f32_e32 v99, v99
	v_lshlrev_b32_e32 v254, 16, v172
	v_and_b32_e32 v255, 0xffff0000, v172
	v_mul_f32_e32 v100, v100, v254
	v_mul_f32_e32 v101, v101, v255
	v_lshlrev_b32_e32 v254, 16, v182
	v_and_b32_e32 v255, 0xffff0000, v182
	v_mul_f32_e32 v100, v100, v254
	v_mul_f32_e32 v101, v101, v255
	v_cvt_pk_bf16_f32 v182, v100, v101
	v_lshlrev_b32_e32 v254, 16, v173
	v_and_b32_e32 v255, 0xffff0000, v173
	v_mul_f32_e32 v102, v102, v254
	v_mul_f32_e32 v103, v103, v255
	v_lshlrev_b32_e32 v254, 16, v183
	v_and_b32_e32 v255, 0xffff0000, v183
	v_mul_f32_e32 v102, v102, v254
	v_mul_f32_e32 v103, v103, v255
	v_cvt_pk_bf16_f32 v183, v102, v103
	v_lshlrev_b32_e32 v254, 16, v174
	v_and_b32_e32 v255, 0xffff0000, v174
	v_mul_f32_e32 v96, v96, v254
	v_mul_f32_e32 v97, v97, v255
	v_lshlrev_b32_e32 v254, 16, v184
	v_and_b32_e32 v255, 0xffff0000, v184
	v_mul_f32_e32 v96, v96, v254
	v_mul_f32_e32 v97, v97, v255
	v_cvt_pk_bf16_f32 v184, v96, v97
	v_lshlrev_b32_e32 v254, 16, v175
	v_and_b32_e32 v255, 0xffff0000, v175
	v_mul_f32_e32 v98, v98, v254
	v_mul_f32_e32 v99, v99, v255
	v_lshlrev_b32_e32 v254, 16, v185
	v_and_b32_e32 v255, 0xffff0000, v185
	v_mul_f32_e32 v98, v98, v254
	v_mul_f32_e32 v99, v99, v255
	v_cvt_pk_bf16_f32 v185, v98, v99
	s_mov_b64 s[100:101], 0x18000
	v_lshl_add_u64 v[190:191], v[248:249], 0, s[100:101]
	global_store_dwordx4 v[190:191], v[182:185], off
	s_mov_b64 s[100:101], 0x18000
	v_lshl_add_u64 v[250:251], v[246:247], 0, s[100:101]
	v_lshl_add_u64 v[252:253], v[248:249], 0, s[100:101]
	global_load_dwordx4 v[172:175], v[250:251], off offset:256
	global_load_dwordx4 v[182:185], v[252:253], off offset:256
	s_waitcnt vmcnt(18)
	v_pk_add_f32 v[92:93], v[92:93], v[108:109]
	v_pk_add_f32 v[94:95], v[94:95], v[110:111]
	v_pk_add_f32 v[88:89], v[88:89], v[104:105]
	v_pk_add_f32 v[90:91], v[90:91], v[106:107]
	v_mul_f32_e32 v92, 0xbfb8aa3b, v92
	v_mul_f32_e32 v93, 0xbfb8aa3b, v93
	v_mul_f32_e32 v94, 0xbfb8aa3b, v94
	v_mul_f32_e32 v95, 0xbfb8aa3b, v95
	v_mul_f32_e32 v88, 0xbfb8aa3b, v88
	v_mul_f32_e32 v89, 0xbfb8aa3b, v89
	v_mul_f32_e32 v90, 0xbfb8aa3b, v90
	v_mul_f32_e32 v91, 0xbfb8aa3b, v91
	v_exp_f32_e32 v92, v92
	v_exp_f32_e32 v93, v93
	v_exp_f32_e32 v94, v94
	v_exp_f32_e32 v95, v95
	v_exp_f32_e32 v88, v88
	v_exp_f32_e32 v89, v89
	v_exp_f32_e32 v90, v90
	v_exp_f32_e32 v91, v91
	v_add_f32_e32 v92, 1.0, v92
	v_add_f32_e32 v93, 1.0, v93
	v_add_f32_e32 v94, 1.0, v94
	v_add_f32_e32 v95, 1.0, v95
	v_add_f32_e32 v88, 1.0, v88
	v_add_f32_e32 v89, 1.0, v89
	v_add_f32_e32 v90, 1.0, v90
	v_add_f32_e32 v91, 1.0, v91
	v_rcp_f32_e32 v92, v92
	v_rcp_f32_e32 v93, v93
	v_rcp_f32_e32 v94, v94
	v_rcp_f32_e32 v95, v95
	v_rcp_f32_e32 v88, v88
	v_rcp_f32_e32 v89, v89
	v_rcp_f32_e32 v90, v90
	v_rcp_f32_e32 v91, v91
	v_lshlrev_b32_e32 v254, 16, v186
	v_and_b32_e32 v255, 0xffff0000, v186
	v_mul_f32_e32 v92, v92, v254
	v_mul_f32_e32 v93, v93, v255
	v_lshlrev_b32_e32 v254, 16, v194
	v_and_b32_e32 v255, 0xffff0000, v194
	v_mul_f32_e32 v92, v92, v254
	v_mul_f32_e32 v93, v93, v255
	v_cvt_pk_bf16_f32 v194, v92, v93
	v_lshlrev_b32_e32 v254, 16, v187
	v_and_b32_e32 v255, 0xffff0000, v187
	v_mul_f32_e32 v94, v94, v254
	v_mul_f32_e32 v95, v95, v255
	v_lshlrev_b32_e32 v254, 16, v195
	v_and_b32_e32 v255, 0xffff0000, v195
	v_mul_f32_e32 v94, v94, v254
	v_mul_f32_e32 v95, v95, v255
	v_cvt_pk_bf16_f32 v195, v94, v95
	v_lshlrev_b32_e32 v254, 16, v188
	v_and_b32_e32 v255, 0xffff0000, v188
	v_mul_f32_e32 v88, v88, v254
	v_mul_f32_e32 v89, v89, v255
	v_lshlrev_b32_e32 v254, 16, v196
	v_and_b32_e32 v255, 0xffff0000, v196
	v_mul_f32_e32 v88, v88, v254
	v_mul_f32_e32 v89, v89, v255
	v_cvt_pk_bf16_f32 v196, v88, v89
	v_lshlrev_b32_e32 v254, 16, v189
	v_and_b32_e32 v255, 0xffff0000, v189
	v_mul_f32_e32 v90, v90, v254
	v_mul_f32_e32 v91, v91, v255
	v_lshlrev_b32_e32 v254, 16, v197
	v_and_b32_e32 v255, 0xffff0000, v197
	v_mul_f32_e32 v90, v90, v254
	v_mul_f32_e32 v91, v91, v255
	v_cvt_pk_bf16_f32 v197, v90, v91
	s_mov_b64 s[100:101], 0x40000
	v_lshl_add_u64 v[190:191], v[248:249], 0, s[100:101]
	global_store_dwordx4 v[190:191], v[194:197], off
	s_mov_b64 s[100:101], 0x40000
	v_lshl_add_u64 v[250:251], v[246:247], 0, s[100:101]
	v_lshl_add_u64 v[252:253], v[248:249], 0, s[100:101]
	global_load_dwordx4 v[186:189], v[250:251], off offset:256
	global_load_dwordx4 v[194:197], v[252:253], off offset:256
	s_waitcnt vmcnt(19)
	v_pk_add_f32 v[84:85], v[84:85], v[108:109]
	v_pk_add_f32 v[86:87], v[86:87], v[110:111]
	v_pk_add_f32 v[80:81], v[80:81], v[104:105]
	v_pk_add_f32 v[82:83], v[82:83], v[106:107]
	v_mul_f32_e32 v84, 0xbfb8aa3b, v84
	v_mul_f32_e32 v85, 0xbfb8aa3b, v85
	v_mul_f32_e32 v86, 0xbfb8aa3b, v86
	v_mul_f32_e32 v87, 0xbfb8aa3b, v87
	v_mul_f32_e32 v80, 0xbfb8aa3b, v80
	v_mul_f32_e32 v81, 0xbfb8aa3b, v81
	v_mul_f32_e32 v82, 0xbfb8aa3b, v82
	v_mul_f32_e32 v83, 0xbfb8aa3b, v83
	v_exp_f32_e32 v84, v84
	v_exp_f32_e32 v85, v85
	v_exp_f32_e32 v86, v86
	v_exp_f32_e32 v87, v87
	v_exp_f32_e32 v80, v80
	v_exp_f32_e32 v81, v81
	v_exp_f32_e32 v82, v82
	v_exp_f32_e32 v83, v83
	v_add_f32_e32 v84, 1.0, v84
	v_add_f32_e32 v85, 1.0, v85
	v_add_f32_e32 v86, 1.0, v86
	v_add_f32_e32 v87, 1.0, v87
	v_add_f32_e32 v80, 1.0, v80
	v_add_f32_e32 v81, 1.0, v81
	v_add_f32_e32 v82, 1.0, v82
	v_add_f32_e32 v83, 1.0, v83
	v_rcp_f32_e32 v84, v84
	v_rcp_f32_e32 v85, v85
	v_rcp_f32_e32 v86, v86
	v_rcp_f32_e32 v87, v87
	v_rcp_f32_e32 v80, v80
	v_rcp_f32_e32 v81, v81
	v_rcp_f32_e32 v82, v82
	v_rcp_f32_e32 v83, v83
	v_lshlrev_b32_e32 v254, 16, v198
	v_and_b32_e32 v255, 0xffff0000, v198
	v_mul_f32_e32 v84, v84, v254
	v_mul_f32_e32 v85, v85, v255
	v_lshlrev_b32_e32 v254, 16, v208
	v_and_b32_e32 v255, 0xffff0000, v208
	v_mul_f32_e32 v84, v84, v254
	v_mul_f32_e32 v85, v85, v255
	v_cvt_pk_bf16_f32 v208, v84, v85
	v_lshlrev_b32_e32 v254, 16, v199
	v_and_b32_e32 v255, 0xffff0000, v199
	v_mul_f32_e32 v86, v86, v254
	v_mul_f32_e32 v87, v87, v255
	v_lshlrev_b32_e32 v254, 16, v209
	v_and_b32_e32 v255, 0xffff0000, v209
	v_mul_f32_e32 v86, v86, v254
	v_mul_f32_e32 v87, v87, v255
	v_cvt_pk_bf16_f32 v209, v86, v87
	v_lshlrev_b32_e32 v254, 16, v200
	v_and_b32_e32 v255, 0xffff0000, v200
	v_mul_f32_e32 v80, v80, v254
	v_mul_f32_e32 v81, v81, v255
	v_lshlrev_b32_e32 v254, 16, v210
	v_and_b32_e32 v255, 0xffff0000, v210
	v_mul_f32_e32 v80, v80, v254
	v_mul_f32_e32 v81, v81, v255
	v_cvt_pk_bf16_f32 v210, v80, v81
	v_lshlrev_b32_e32 v254, 16, v201
	v_and_b32_e32 v255, 0xffff0000, v201
	v_mul_f32_e32 v82, v82, v254
	v_mul_f32_e32 v83, v83, v255
	v_lshlrev_b32_e32 v254, 16, v211
	v_and_b32_e32 v255, 0xffff0000, v211
	v_mul_f32_e32 v82, v82, v254
	v_mul_f32_e32 v83, v83, v255
	v_cvt_pk_bf16_f32 v211, v82, v83
	s_mov_b64 s[100:101], 0x48000
	v_lshl_add_u64 v[190:191], v[248:249], 0, s[100:101]
	global_store_dwordx4 v[190:191], v[208:211], off
	s_mov_b64 s[100:101], 0x48000
	v_lshl_add_u64 v[250:251], v[246:247], 0, s[100:101]
	v_lshl_add_u64 v[252:253], v[248:249], 0, s[100:101]
	global_load_dwordx4 v[198:201], v[250:251], off offset:256
	global_load_dwordx4 v[208:211], v[252:253], off offset:256
	s_waitcnt vmcnt(20)
	v_pk_add_f32 v[76:77], v[76:77], v[108:109]
	v_pk_add_f32 v[78:79], v[78:79], v[110:111]
	v_pk_add_f32 v[72:73], v[72:73], v[104:105]
	v_pk_add_f32 v[74:75], v[74:75], v[106:107]
	v_mul_f32_e32 v76, 0xbfb8aa3b, v76
	v_mul_f32_e32 v77, 0xbfb8aa3b, v77
	v_mul_f32_e32 v78, 0xbfb8aa3b, v78
	v_mul_f32_e32 v79, 0xbfb8aa3b, v79
	v_mul_f32_e32 v72, 0xbfb8aa3b, v72
	v_mul_f32_e32 v73, 0xbfb8aa3b, v73
	v_mul_f32_e32 v74, 0xbfb8aa3b, v74
	v_mul_f32_e32 v75, 0xbfb8aa3b, v75
	v_exp_f32_e32 v76, v76
	v_exp_f32_e32 v77, v77
	v_exp_f32_e32 v78, v78
	v_exp_f32_e32 v79, v79
	v_exp_f32_e32 v72, v72
	v_exp_f32_e32 v73, v73
	v_exp_f32_e32 v74, v74
	v_exp_f32_e32 v75, v75
	v_add_f32_e32 v76, 1.0, v76
	v_add_f32_e32 v77, 1.0, v77
	v_add_f32_e32 v78, 1.0, v78
	v_add_f32_e32 v79, 1.0, v79
	v_add_f32_e32 v72, 1.0, v72
	v_add_f32_e32 v73, 1.0, v73
	v_add_f32_e32 v74, 1.0, v74
	v_add_f32_e32 v75, 1.0, v75
	v_rcp_f32_e32 v76, v76
	v_rcp_f32_e32 v77, v77
	v_rcp_f32_e32 v78, v78
	v_rcp_f32_e32 v79, v79
	v_rcp_f32_e32 v72, v72
	v_rcp_f32_e32 v73, v73
	v_rcp_f32_e32 v74, v74
	v_rcp_f32_e32 v75, v75
	v_lshlrev_b32_e32 v254, 16, v212
	v_and_b32_e32 v255, 0xffff0000, v212
	v_mul_f32_e32 v76, v76, v254
	v_mul_f32_e32 v77, v77, v255
	v_lshlrev_b32_e32 v254, 16, v216
	v_and_b32_e32 v255, 0xffff0000, v216
	v_mul_f32_e32 v76, v76, v254
	v_mul_f32_e32 v77, v77, v255
	v_cvt_pk_bf16_f32 v216, v76, v77
	v_lshlrev_b32_e32 v254, 16, v213
	v_and_b32_e32 v255, 0xffff0000, v213
	v_mul_f32_e32 v78, v78, v254
	v_mul_f32_e32 v79, v79, v255
	v_lshlrev_b32_e32 v254, 16, v217
	v_and_b32_e32 v255, 0xffff0000, v217
	v_mul_f32_e32 v78, v78, v254
	v_mul_f32_e32 v79, v79, v255
	v_cvt_pk_bf16_f32 v217, v78, v79
	v_lshlrev_b32_e32 v254, 16, v214
	v_and_b32_e32 v255, 0xffff0000, v214
	v_mul_f32_e32 v72, v72, v254
	v_mul_f32_e32 v73, v73, v255
	v_lshlrev_b32_e32 v254, 16, v218
	v_and_b32_e32 v255, 0xffff0000, v218
	v_mul_f32_e32 v72, v72, v254
	v_mul_f32_e32 v73, v73, v255
	v_cvt_pk_bf16_f32 v218, v72, v73
	v_lshlrev_b32_e32 v254, 16, v215
	v_and_b32_e32 v255, 0xffff0000, v215
	v_mul_f32_e32 v74, v74, v254
	v_mul_f32_e32 v75, v75, v255
	v_lshlrev_b32_e32 v254, 16, v219
	v_and_b32_e32 v255, 0xffff0000, v219
	v_mul_f32_e32 v74, v74, v254
	v_mul_f32_e32 v75, v75, v255
	v_cvt_pk_bf16_f32 v219, v74, v75
	s_mov_b64 s[100:101], 0x50000
	v_lshl_add_u64 v[190:191], v[248:249], 0, s[100:101]
	global_store_dwordx4 v[190:191], v[216:219], off
	s_mov_b64 s[100:101], 0x50000
	v_lshl_add_u64 v[250:251], v[246:247], 0, s[100:101]
	v_lshl_add_u64 v[252:253], v[248:249], 0, s[100:101]
	global_load_dwordx4 v[212:215], v[250:251], off offset:256
	global_load_dwordx4 v[216:219], v[252:253], off offset:256
	s_waitcnt vmcnt(21)
	v_pk_add_f32 v[68:69], v[68:69], v[108:109]
	v_pk_add_f32 v[70:71], v[70:71], v[110:111]
	v_pk_add_f32 v[64:65], v[64:65], v[104:105]
	v_pk_add_f32 v[66:67], v[66:67], v[106:107]
	v_mul_f32_e32 v68, 0xbfb8aa3b, v68
	v_mul_f32_e32 v69, 0xbfb8aa3b, v69
	v_mul_f32_e32 v70, 0xbfb8aa3b, v70
	v_mul_f32_e32 v71, 0xbfb8aa3b, v71
	v_mul_f32_e32 v64, 0xbfb8aa3b, v64
	v_mul_f32_e32 v65, 0xbfb8aa3b, v65
	v_mul_f32_e32 v66, 0xbfb8aa3b, v66
	v_mul_f32_e32 v67, 0xbfb8aa3b, v67
	v_exp_f32_e32 v68, v68
	v_exp_f32_e32 v69, v69
	v_exp_f32_e32 v70, v70
	v_exp_f32_e32 v71, v71
	v_exp_f32_e32 v64, v64
	v_exp_f32_e32 v65, v65
	v_exp_f32_e32 v66, v66
	v_exp_f32_e32 v67, v67
	v_add_f32_e32 v68, 1.0, v68
	v_add_f32_e32 v69, 1.0, v69
	v_add_f32_e32 v70, 1.0, v70
	v_add_f32_e32 v71, 1.0, v71
	v_add_f32_e32 v64, 1.0, v64
	v_add_f32_e32 v65, 1.0, v65
	v_add_f32_e32 v66, 1.0, v66
	v_add_f32_e32 v67, 1.0, v67
	v_rcp_f32_e32 v68, v68
	v_rcp_f32_e32 v69, v69
	v_rcp_f32_e32 v70, v70
	v_rcp_f32_e32 v71, v71
	v_rcp_f32_e32 v64, v64
	v_rcp_f32_e32 v65, v65
	v_rcp_f32_e32 v66, v66
	v_rcp_f32_e32 v67, v67
	v_lshlrev_b32_e32 v254, 16, v220
	v_and_b32_e32 v255, 0xffff0000, v220
	v_mul_f32_e32 v68, v68, v254
	v_mul_f32_e32 v69, v69, v255
	v_lshlrev_b32_e32 v254, 16, v232
	v_and_b32_e32 v255, 0xffff0000, v232
	v_mul_f32_e32 v68, v68, v254
	v_mul_f32_e32 v69, v69, v255
	v_cvt_pk_bf16_f32 v232, v68, v69
	v_lshlrev_b32_e32 v254, 16, v221
	v_and_b32_e32 v255, 0xffff0000, v221
	v_mul_f32_e32 v70, v70, v254
	v_mul_f32_e32 v71, v71, v255
	v_lshlrev_b32_e32 v254, 16, v233
	v_and_b32_e32 v255, 0xffff0000, v233
	v_mul_f32_e32 v70, v70, v254
	v_mul_f32_e32 v71, v71, v255
	v_cvt_pk_bf16_f32 v233, v70, v71
	v_lshlrev_b32_e32 v254, 16, v222
	v_and_b32_e32 v255, 0xffff0000, v222
	v_mul_f32_e32 v64, v64, v254
	v_mul_f32_e32 v65, v65, v255
	v_lshlrev_b32_e32 v254, 16, v234
	v_and_b32_e32 v255, 0xffff0000, v234
	v_mul_f32_e32 v64, v64, v254
	v_mul_f32_e32 v65, v65, v255
	v_cvt_pk_bf16_f32 v234, v64, v65
	v_lshlrev_b32_e32 v254, 16, v223
	v_and_b32_e32 v255, 0xffff0000, v223
	v_mul_f32_e32 v66, v66, v254
	v_mul_f32_e32 v67, v67, v255
	v_lshlrev_b32_e32 v254, 16, v235
	v_and_b32_e32 v255, 0xffff0000, v235
	v_mul_f32_e32 v66, v66, v254
	v_mul_f32_e32 v67, v67, v255
	v_cvt_pk_bf16_f32 v235, v66, v67
	s_mov_b64 s[100:101], 0x58000
	v_lshl_add_u64 v[190:191], v[248:249], 0, s[100:101]
	global_store_dwordx4 v[190:191], v[232:235], off
	s_mov_b64 s[100:101], 0x58000
	v_lshl_add_u64 v[250:251], v[246:247], 0, s[100:101]
	v_lshl_add_u64 v[252:253], v[248:249], 0, s[100:101]
	global_load_dwordx4 v[220:223], v[250:251], off offset:256
	global_load_dwordx4 v[232:235], v[252:253], off offset:256
	s_waitcnt vmcnt(21)
	v_pk_add_f32 v[60:61], v[60:61], v[236:237]
	v_pk_add_f32 v[62:63], v[62:63], v[238:239]
	v_pk_add_f32 v[56:57], v[56:57], v[242:243]
	v_pk_add_f32 v[58:59], v[58:59], v[244:245]
	v_mul_f32_e32 v60, 0xbfb8aa3b, v60
	v_mul_f32_e32 v61, 0xbfb8aa3b, v61
	v_mul_f32_e32 v62, 0xbfb8aa3b, v62
	v_mul_f32_e32 v63, 0xbfb8aa3b, v63
	v_mul_f32_e32 v56, 0xbfb8aa3b, v56
	v_mul_f32_e32 v57, 0xbfb8aa3b, v57
	v_mul_f32_e32 v58, 0xbfb8aa3b, v58
	v_mul_f32_e32 v59, 0xbfb8aa3b, v59
	v_exp_f32_e32 v60, v60
	v_exp_f32_e32 v61, v61
	v_exp_f32_e32 v62, v62
	v_exp_f32_e32 v63, v63
	v_exp_f32_e32 v56, v56
	v_exp_f32_e32 v57, v57
	v_exp_f32_e32 v58, v58
	v_exp_f32_e32 v59, v59
	v_add_f32_e32 v60, 1.0, v60
	v_add_f32_e32 v61, 1.0, v61
	v_add_f32_e32 v62, 1.0, v62
	v_add_f32_e32 v63, 1.0, v63
	v_add_f32_e32 v56, 1.0, v56
	v_add_f32_e32 v57, 1.0, v57
	v_add_f32_e32 v58, 1.0, v58
	v_add_f32_e32 v59, 1.0, v59
	v_rcp_f32_e32 v60, v60
	v_rcp_f32_e32 v61, v61
	v_rcp_f32_e32 v62, v62
	v_rcp_f32_e32 v63, v63
	v_rcp_f32_e32 v56, v56
	v_rcp_f32_e32 v57, v57
	v_rcp_f32_e32 v58, v58
	v_rcp_f32_e32 v59, v59
	v_lshlrev_b32_e32 v254, 16, v136
	v_and_b32_e32 v255, 0xffff0000, v136
	v_mul_f32_e32 v60, v60, v254
	v_mul_f32_e32 v61, v61, v255
	v_lshlrev_b32_e32 v254, 16, v140
	v_and_b32_e32 v255, 0xffff0000, v140
	v_mul_f32_e32 v60, v60, v254
	v_mul_f32_e32 v61, v61, v255
	v_cvt_pk_bf16_f32 v140, v60, v61
	v_lshlrev_b32_e32 v254, 16, v137
	v_and_b32_e32 v255, 0xffff0000, v137
	v_mul_f32_e32 v62, v62, v254
	v_mul_f32_e32 v63, v63, v255
	v_lshlrev_b32_e32 v254, 16, v141
	v_and_b32_e32 v255, 0xffff0000, v141
	v_mul_f32_e32 v62, v62, v254
	v_mul_f32_e32 v63, v63, v255
	v_cvt_pk_bf16_f32 v141, v62, v63
	v_lshlrev_b32_e32 v254, 16, v138
	v_and_b32_e32 v255, 0xffff0000, v138
	v_mul_f32_e32 v56, v56, v254
	v_mul_f32_e32 v57, v57, v255
	v_lshlrev_b32_e32 v254, 16, v142
	v_and_b32_e32 v255, 0xffff0000, v142
	v_mul_f32_e32 v56, v56, v254
	v_mul_f32_e32 v57, v57, v255
	v_cvt_pk_bf16_f32 v142, v56, v57
	v_lshlrev_b32_e32 v254, 16, v139
	v_and_b32_e32 v255, 0xffff0000, v139
	v_mul_f32_e32 v58, v58, v254
	v_mul_f32_e32 v59, v59, v255
	v_lshlrev_b32_e32 v254, 16, v143
	v_and_b32_e32 v255, 0xffff0000, v143
	v_mul_f32_e32 v58, v58, v254
	v_mul_f32_e32 v59, v59, v255
	v_cvt_pk_bf16_f32 v143, v58, v59
	global_store_dwordx4 v[248:249], v[140:143], off offset:256
	s_waitcnt vmcnt(19)
	v_pk_add_f32 v[52:53], v[52:53], v[236:237]
	v_pk_add_f32 v[54:55], v[54:55], v[238:239]
	v_pk_add_f32 v[48:49], v[48:49], v[242:243]
	v_pk_add_f32 v[50:51], v[50:51], v[244:245]
	v_mul_f32_e32 v52, 0xbfb8aa3b, v52
	v_mul_f32_e32 v53, 0xbfb8aa3b, v53
	v_mul_f32_e32 v54, 0xbfb8aa3b, v54
	v_mul_f32_e32 v55, 0xbfb8aa3b, v55
	v_mul_f32_e32 v48, 0xbfb8aa3b, v48
	v_mul_f32_e32 v49, 0xbfb8aa3b, v49
	v_mul_f32_e32 v50, 0xbfb8aa3b, v50
	v_mul_f32_e32 v51, 0xbfb8aa3b, v51
	v_exp_f32_e32 v52, v52
	v_exp_f32_e32 v53, v53
	v_exp_f32_e32 v54, v54
	v_exp_f32_e32 v55, v55
	v_exp_f32_e32 v48, v48
	v_exp_f32_e32 v49, v49
	v_exp_f32_e32 v50, v50
	v_exp_f32_e32 v51, v51
	v_add_f32_e32 v52, 1.0, v52
	v_add_f32_e32 v53, 1.0, v53
	v_add_f32_e32 v54, 1.0, v54
	v_add_f32_e32 v55, 1.0, v55
	v_add_f32_e32 v48, 1.0, v48
	v_add_f32_e32 v49, 1.0, v49
	v_add_f32_e32 v50, 1.0, v50
	v_add_f32_e32 v51, 1.0, v51
	v_rcp_f32_e32 v52, v52
	v_rcp_f32_e32 v53, v53
	v_rcp_f32_e32 v54, v54
	v_rcp_f32_e32 v55, v55
	v_rcp_f32_e32 v48, v48
	v_rcp_f32_e32 v49, v49
	v_rcp_f32_e32 v50, v50
	v_rcp_f32_e32 v51, v51
	v_lshlrev_b32_e32 v254, 16, v144
	v_and_b32_e32 v255, 0xffff0000, v144
	v_mul_f32_e32 v52, v52, v254
	v_mul_f32_e32 v53, v53, v255
	v_lshlrev_b32_e32 v254, 16, v160
	v_and_b32_e32 v255, 0xffff0000, v160
	v_mul_f32_e32 v52, v52, v254
	v_mul_f32_e32 v53, v53, v255
	v_cvt_pk_bf16_f32 v160, v52, v53
	v_lshlrev_b32_e32 v254, 16, v145
	v_and_b32_e32 v255, 0xffff0000, v145
	v_mul_f32_e32 v54, v54, v254
	v_mul_f32_e32 v55, v55, v255
	v_lshlrev_b32_e32 v254, 16, v161
	v_and_b32_e32 v255, 0xffff0000, v161
	v_mul_f32_e32 v54, v54, v254
	v_mul_f32_e32 v55, v55, v255
	v_cvt_pk_bf16_f32 v161, v54, v55
	v_lshlrev_b32_e32 v254, 16, v146
	v_and_b32_e32 v255, 0xffff0000, v146
	v_mul_f32_e32 v48, v48, v254
	v_mul_f32_e32 v49, v49, v255
	v_lshlrev_b32_e32 v254, 16, v162
	v_and_b32_e32 v255, 0xffff0000, v162
	v_mul_f32_e32 v48, v48, v254
	v_mul_f32_e32 v49, v49, v255
	v_cvt_pk_bf16_f32 v162, v48, v49
	v_lshlrev_b32_e32 v254, 16, v147
	v_and_b32_e32 v255, 0xffff0000, v147
	v_mul_f32_e32 v50, v50, v254
	v_mul_f32_e32 v51, v51, v255
	v_lshlrev_b32_e32 v254, 16, v163
	v_and_b32_e32 v255, 0xffff0000, v163
	v_mul_f32_e32 v50, v50, v254
	v_mul_f32_e32 v51, v51, v255
	v_cvt_pk_bf16_f32 v163, v50, v51
	s_mov_b64 s[100:101], 0x8000
	v_lshl_add_u64 v[190:191], v[248:249], 0, s[100:101]
	global_store_dwordx4 v[190:191], v[160:163], off offset:256
	s_waitcnt vmcnt(17)
	v_pk_add_f32 v[44:45], v[44:45], v[236:237]
	v_pk_add_f32 v[46:47], v[46:47], v[238:239]
	v_pk_add_f32 v[40:41], v[40:41], v[242:243]
	v_pk_add_f32 v[42:43], v[42:43], v[244:245]
	v_mul_f32_e32 v44, 0xbfb8aa3b, v44
	v_mul_f32_e32 v45, 0xbfb8aa3b, v45
	v_mul_f32_e32 v46, 0xbfb8aa3b, v46
	v_mul_f32_e32 v47, 0xbfb8aa3b, v47
	v_mul_f32_e32 v40, 0xbfb8aa3b, v40
	v_mul_f32_e32 v41, 0xbfb8aa3b, v41
	v_mul_f32_e32 v42, 0xbfb8aa3b, v42
	v_mul_f32_e32 v43, 0xbfb8aa3b, v43
	v_exp_f32_e32 v44, v44
	v_exp_f32_e32 v45, v45
	v_exp_f32_e32 v46, v46
	v_exp_f32_e32 v47, v47
	v_exp_f32_e32 v40, v40
	v_exp_f32_e32 v41, v41
	v_exp_f32_e32 v42, v42
	v_exp_f32_e32 v43, v43
	v_add_f32_e32 v44, 1.0, v44
	v_add_f32_e32 v45, 1.0, v45
	v_add_f32_e32 v46, 1.0, v46
	v_add_f32_e32 v47, 1.0, v47
	v_add_f32_e32 v40, 1.0, v40
	v_add_f32_e32 v41, 1.0, v41
	v_add_f32_e32 v42, 1.0, v42
	v_add_f32_e32 v43, 1.0, v43
	v_rcp_f32_e32 v44, v44
	v_rcp_f32_e32 v45, v45
	v_rcp_f32_e32 v46, v46
	v_rcp_f32_e32 v47, v47
	v_rcp_f32_e32 v40, v40
	v_rcp_f32_e32 v41, v41
	v_rcp_f32_e32 v42, v42
	v_rcp_f32_e32 v43, v43
	v_lshlrev_b32_e32 v254, 16, v164
	v_and_b32_e32 v255, 0xffff0000, v164
	v_mul_f32_e32 v44, v44, v254
	v_mul_f32_e32 v45, v45, v255
	v_lshlrev_b32_e32 v254, 16, v168
	v_and_b32_e32 v255, 0xffff0000, v168
	v_mul_f32_e32 v44, v44, v254
	v_mul_f32_e32 v45, v45, v255
	v_cvt_pk_bf16_f32 v168, v44, v45
	v_lshlrev_b32_e32 v254, 16, v165
	v_and_b32_e32 v255, 0xffff0000, v165
	v_mul_f32_e32 v46, v46, v254
	v_mul_f32_e32 v47, v47, v255
	v_lshlrev_b32_e32 v254, 16, v169
	v_and_b32_e32 v255, 0xffff0000, v169
	v_mul_f32_e32 v46, v46, v254
	v_mul_f32_e32 v47, v47, v255
	v_cvt_pk_bf16_f32 v169, v46, v47
	v_lshlrev_b32_e32 v254, 16, v166
	v_and_b32_e32 v255, 0xffff0000, v166
	v_mul_f32_e32 v40, v40, v254
	v_mul_f32_e32 v41, v41, v255
	v_lshlrev_b32_e32 v254, 16, v170
	v_and_b32_e32 v255, 0xffff0000, v170
	v_mul_f32_e32 v40, v40, v254
	v_mul_f32_e32 v41, v41, v255
	v_cvt_pk_bf16_f32 v170, v40, v41
	v_lshlrev_b32_e32 v254, 16, v167
	v_and_b32_e32 v255, 0xffff0000, v167
	v_mul_f32_e32 v42, v42, v254
	v_mul_f32_e32 v43, v43, v255
	v_lshlrev_b32_e32 v254, 16, v171
	v_and_b32_e32 v255, 0xffff0000, v171
	v_mul_f32_e32 v42, v42, v254
	v_mul_f32_e32 v43, v43, v255
	v_cvt_pk_bf16_f32 v171, v42, v43
	s_mov_b64 s[100:101], 0x10000
	v_lshl_add_u64 v[190:191], v[248:249], 0, s[100:101]
	global_store_dwordx4 v[190:191], v[168:171], off offset:256
	s_waitcnt vmcnt(15)
	v_pk_add_f32 v[36:37], v[36:37], v[236:237]
	v_pk_add_f32 v[38:39], v[38:39], v[238:239]
	v_pk_add_f32 v[32:33], v[32:33], v[242:243]
	v_pk_add_f32 v[34:35], v[34:35], v[244:245]
	v_mul_f32_e32 v36, 0xbfb8aa3b, v36
	v_mul_f32_e32 v37, 0xbfb8aa3b, v37
	v_mul_f32_e32 v38, 0xbfb8aa3b, v38
	v_mul_f32_e32 v39, 0xbfb8aa3b, v39
	v_mul_f32_e32 v32, 0xbfb8aa3b, v32
	v_mul_f32_e32 v33, 0xbfb8aa3b, v33
	v_mul_f32_e32 v34, 0xbfb8aa3b, v34
	v_mul_f32_e32 v35, 0xbfb8aa3b, v35
	v_exp_f32_e32 v36, v36
	v_exp_f32_e32 v37, v37
	v_exp_f32_e32 v38, v38
	v_exp_f32_e32 v39, v39
	v_exp_f32_e32 v32, v32
	v_exp_f32_e32 v33, v33
	v_exp_f32_e32 v34, v34
	v_exp_f32_e32 v35, v35
	v_add_f32_e32 v36, 1.0, v36
	v_add_f32_e32 v37, 1.0, v37
	v_add_f32_e32 v38, 1.0, v38
	v_add_f32_e32 v39, 1.0, v39
	v_add_f32_e32 v32, 1.0, v32
	v_add_f32_e32 v33, 1.0, v33
	v_add_f32_e32 v34, 1.0, v34
	v_add_f32_e32 v35, 1.0, v35
	v_rcp_f32_e32 v36, v36
	v_rcp_f32_e32 v37, v37
	v_rcp_f32_e32 v38, v38
	v_rcp_f32_e32 v39, v39
	v_rcp_f32_e32 v32, v32
	v_rcp_f32_e32 v33, v33
	v_rcp_f32_e32 v34, v34
	v_rcp_f32_e32 v35, v35
	v_lshlrev_b32_e32 v254, 16, v172
	v_and_b32_e32 v255, 0xffff0000, v172
	v_mul_f32_e32 v36, v36, v254
	v_mul_f32_e32 v37, v37, v255
	v_lshlrev_b32_e32 v254, 16, v182
	v_and_b32_e32 v255, 0xffff0000, v182
	v_mul_f32_e32 v36, v36, v254
	v_mul_f32_e32 v37, v37, v255
	v_cvt_pk_bf16_f32 v182, v36, v37
	v_lshlrev_b32_e32 v254, 16, v173
	v_and_b32_e32 v255, 0xffff0000, v173
	v_mul_f32_e32 v38, v38, v254
	v_mul_f32_e32 v39, v39, v255
	v_lshlrev_b32_e32 v254, 16, v183
	v_and_b32_e32 v255, 0xffff0000, v183
	v_mul_f32_e32 v38, v38, v254
	v_mul_f32_e32 v39, v39, v255
	v_cvt_pk_bf16_f32 v183, v38, v39
	v_lshlrev_b32_e32 v254, 16, v174
	v_and_b32_e32 v255, 0xffff0000, v174
	v_mul_f32_e32 v32, v32, v254
	v_mul_f32_e32 v33, v33, v255
	v_lshlrev_b32_e32 v254, 16, v184
	v_and_b32_e32 v255, 0xffff0000, v184
	v_mul_f32_e32 v32, v32, v254
	v_mul_f32_e32 v33, v33, v255
	v_cvt_pk_bf16_f32 v184, v32, v33
	v_lshlrev_b32_e32 v254, 16, v175
	v_and_b32_e32 v255, 0xffff0000, v175
	v_mul_f32_e32 v34, v34, v254
	v_mul_f32_e32 v35, v35, v255
	v_lshlrev_b32_e32 v254, 16, v185
	v_and_b32_e32 v255, 0xffff0000, v185
	v_mul_f32_e32 v34, v34, v254
	v_mul_f32_e32 v35, v35, v255
	v_cvt_pk_bf16_f32 v185, v34, v35
	s_mov_b64 s[100:101], 0x18000
	v_lshl_add_u64 v[190:191], v[248:249], 0, s[100:101]
	global_store_dwordx4 v[190:191], v[182:185], off offset:256
	s_waitcnt vmcnt(13)
	v_pk_add_f32 v[28:29], v[28:29], v[236:237]
	v_pk_add_f32 v[30:31], v[30:31], v[238:239]
	v_pk_add_f32 v[24:25], v[24:25], v[242:243]
	v_pk_add_f32 v[26:27], v[26:27], v[244:245]
	v_mul_f32_e32 v28, 0xbfb8aa3b, v28
	v_mul_f32_e32 v29, 0xbfb8aa3b, v29
	v_mul_f32_e32 v30, 0xbfb8aa3b, v30
	v_mul_f32_e32 v31, 0xbfb8aa3b, v31
	v_mul_f32_e32 v24, 0xbfb8aa3b, v24
	v_mul_f32_e32 v25, 0xbfb8aa3b, v25
	v_mul_f32_e32 v26, 0xbfb8aa3b, v26
	v_mul_f32_e32 v27, 0xbfb8aa3b, v27
	v_exp_f32_e32 v28, v28
	v_exp_f32_e32 v29, v29
	v_exp_f32_e32 v30, v30
	v_exp_f32_e32 v31, v31
	v_exp_f32_e32 v24, v24
	v_exp_f32_e32 v25, v25
	v_exp_f32_e32 v26, v26
	v_exp_f32_e32 v27, v27
	v_add_f32_e32 v28, 1.0, v28
	v_add_f32_e32 v29, 1.0, v29
	v_add_f32_e32 v30, 1.0, v30
	v_add_f32_e32 v31, 1.0, v31
	v_add_f32_e32 v24, 1.0, v24
	v_add_f32_e32 v25, 1.0, v25
	v_add_f32_e32 v26, 1.0, v26
	v_add_f32_e32 v27, 1.0, v27
	v_rcp_f32_e32 v28, v28
	v_rcp_f32_e32 v29, v29
	v_rcp_f32_e32 v30, v30
	v_rcp_f32_e32 v31, v31
	v_rcp_f32_e32 v24, v24
	v_rcp_f32_e32 v25, v25
	v_rcp_f32_e32 v26, v26
	v_rcp_f32_e32 v27, v27
	v_lshlrev_b32_e32 v254, 16, v186
	v_and_b32_e32 v255, 0xffff0000, v186
	v_mul_f32_e32 v28, v28, v254
	v_mul_f32_e32 v29, v29, v255
	v_lshlrev_b32_e32 v254, 16, v194
	v_and_b32_e32 v255, 0xffff0000, v194
	v_mul_f32_e32 v28, v28, v254
	v_mul_f32_e32 v29, v29, v255
	v_cvt_pk_bf16_f32 v194, v28, v29
	v_lshlrev_b32_e32 v254, 16, v187
	v_and_b32_e32 v255, 0xffff0000, v187
	v_mul_f32_e32 v30, v30, v254
	v_mul_f32_e32 v31, v31, v255
	v_lshlrev_b32_e32 v254, 16, v195
	v_and_b32_e32 v255, 0xffff0000, v195
	v_mul_f32_e32 v30, v30, v254
	v_mul_f32_e32 v31, v31, v255
	v_cvt_pk_bf16_f32 v195, v30, v31
	v_lshlrev_b32_e32 v254, 16, v188
	v_and_b32_e32 v255, 0xffff0000, v188
	v_mul_f32_e32 v24, v24, v254
	v_mul_f32_e32 v25, v25, v255
	v_lshlrev_b32_e32 v254, 16, v196
	v_and_b32_e32 v255, 0xffff0000, v196
	v_mul_f32_e32 v24, v24, v254
	v_mul_f32_e32 v25, v25, v255
	v_cvt_pk_bf16_f32 v196, v24, v25
	v_lshlrev_b32_e32 v254, 16, v189
	v_and_b32_e32 v255, 0xffff0000, v189
	v_mul_f32_e32 v26, v26, v254
	v_mul_f32_e32 v27, v27, v255
	v_lshlrev_b32_e32 v254, 16, v197
	v_and_b32_e32 v255, 0xffff0000, v197
	v_mul_f32_e32 v26, v26, v254
	v_mul_f32_e32 v27, v27, v255
	v_cvt_pk_bf16_f32 v197, v26, v27
	s_mov_b64 s[100:101], 0x40000
	v_lshl_add_u64 v[190:191], v[248:249], 0, s[100:101]
	global_store_dwordx4 v[190:191], v[194:197], off offset:256
	s_waitcnt vmcnt(11)
	v_pk_add_f32 v[20:21], v[20:21], v[236:237]
	v_pk_add_f32 v[22:23], v[22:23], v[238:239]
	v_pk_add_f32 v[16:17], v[16:17], v[242:243]
	v_pk_add_f32 v[18:19], v[18:19], v[244:245]
	v_mul_f32_e32 v20, 0xbfb8aa3b, v20
	v_mul_f32_e32 v21, 0xbfb8aa3b, v21
	v_mul_f32_e32 v22, 0xbfb8aa3b, v22
	v_mul_f32_e32 v23, 0xbfb8aa3b, v23
	v_mul_f32_e32 v16, 0xbfb8aa3b, v16
	v_mul_f32_e32 v17, 0xbfb8aa3b, v17
	v_mul_f32_e32 v18, 0xbfb8aa3b, v18
	v_mul_f32_e32 v19, 0xbfb8aa3b, v19
	v_exp_f32_e32 v20, v20
	v_exp_f32_e32 v21, v21
	v_exp_f32_e32 v22, v22
	v_exp_f32_e32 v23, v23
	v_exp_f32_e32 v16, v16
	v_exp_f32_e32 v17, v17
	v_exp_f32_e32 v18, v18
	v_exp_f32_e32 v19, v19
	v_add_f32_e32 v20, 1.0, v20
	v_add_f32_e32 v21, 1.0, v21
	v_add_f32_e32 v22, 1.0, v22
	v_add_f32_e32 v23, 1.0, v23
	v_add_f32_e32 v16, 1.0, v16
	v_add_f32_e32 v17, 1.0, v17
	v_add_f32_e32 v18, 1.0, v18
	v_add_f32_e32 v19, 1.0, v19
	v_rcp_f32_e32 v20, v20
	v_rcp_f32_e32 v21, v21
	v_rcp_f32_e32 v22, v22
	v_rcp_f32_e32 v23, v23
	v_rcp_f32_e32 v16, v16
	v_rcp_f32_e32 v17, v17
	v_rcp_f32_e32 v18, v18
	v_rcp_f32_e32 v19, v19
	v_lshlrev_b32_e32 v254, 16, v198
	v_and_b32_e32 v255, 0xffff0000, v198
	v_mul_f32_e32 v20, v20, v254
	v_mul_f32_e32 v21, v21, v255
	v_lshlrev_b32_e32 v254, 16, v208
	v_and_b32_e32 v255, 0xffff0000, v208
	v_mul_f32_e32 v20, v20, v254
	v_mul_f32_e32 v21, v21, v255
	v_cvt_pk_bf16_f32 v208, v20, v21
	v_lshlrev_b32_e32 v254, 16, v199
	v_and_b32_e32 v255, 0xffff0000, v199
	v_mul_f32_e32 v22, v22, v254
	v_mul_f32_e32 v23, v23, v255
	v_lshlrev_b32_e32 v254, 16, v209
	v_and_b32_e32 v255, 0xffff0000, v209
	v_mul_f32_e32 v22, v22, v254
	v_mul_f32_e32 v23, v23, v255
	v_cvt_pk_bf16_f32 v209, v22, v23
	v_lshlrev_b32_e32 v254, 16, v200
	v_and_b32_e32 v255, 0xffff0000, v200
	v_mul_f32_e32 v16, v16, v254
	v_mul_f32_e32 v17, v17, v255
	v_lshlrev_b32_e32 v254, 16, v210
	v_and_b32_e32 v255, 0xffff0000, v210
	v_mul_f32_e32 v16, v16, v254
	v_mul_f32_e32 v17, v17, v255
	v_cvt_pk_bf16_f32 v210, v16, v17
	v_lshlrev_b32_e32 v254, 16, v201
	v_and_b32_e32 v255, 0xffff0000, v201
	v_mul_f32_e32 v18, v18, v254
	v_mul_f32_e32 v19, v19, v255
	v_lshlrev_b32_e32 v254, 16, v211
	v_and_b32_e32 v255, 0xffff0000, v211
	v_mul_f32_e32 v18, v18, v254
	v_mul_f32_e32 v19, v19, v255
	v_cvt_pk_bf16_f32 v211, v18, v19
	s_mov_b64 s[100:101], 0x48000
	v_lshl_add_u64 v[190:191], v[248:249], 0, s[100:101]
	global_store_dwordx4 v[190:191], v[208:211], off offset:256
	s_waitcnt vmcnt(9)
	v_pk_add_f32 v[12:13], v[12:13], v[236:237]
	v_pk_add_f32 v[14:15], v[14:15], v[238:239]
	v_pk_add_f32 v[8:9], v[8:9], v[242:243]
	v_pk_add_f32 v[10:11], v[10:11], v[244:245]
	v_mul_f32_e32 v12, 0xbfb8aa3b, v12
	v_mul_f32_e32 v13, 0xbfb8aa3b, v13
	v_mul_f32_e32 v14, 0xbfb8aa3b, v14
	v_mul_f32_e32 v15, 0xbfb8aa3b, v15
	v_mul_f32_e32 v8, 0xbfb8aa3b, v8
	v_mul_f32_e32 v9, 0xbfb8aa3b, v9
	v_mul_f32_e32 v10, 0xbfb8aa3b, v10
	v_mul_f32_e32 v11, 0xbfb8aa3b, v11
	v_exp_f32_e32 v12, v12
	v_exp_f32_e32 v13, v13
	v_exp_f32_e32 v14, v14
	v_exp_f32_e32 v15, v15
	v_exp_f32_e32 v8, v8
	v_exp_f32_e32 v9, v9
	v_exp_f32_e32 v10, v10
	v_exp_f32_e32 v11, v11
	v_add_f32_e32 v12, 1.0, v12
	v_add_f32_e32 v13, 1.0, v13
	v_add_f32_e32 v14, 1.0, v14
	v_add_f32_e32 v15, 1.0, v15
	v_add_f32_e32 v8, 1.0, v8
	v_add_f32_e32 v9, 1.0, v9
	v_add_f32_e32 v10, 1.0, v10
	v_add_f32_e32 v11, 1.0, v11
	v_rcp_f32_e32 v12, v12
	v_rcp_f32_e32 v13, v13
	v_rcp_f32_e32 v14, v14
	v_rcp_f32_e32 v15, v15
	v_rcp_f32_e32 v8, v8
	v_rcp_f32_e32 v9, v9
	v_rcp_f32_e32 v10, v10
	v_rcp_f32_e32 v11, v11
	v_lshlrev_b32_e32 v254, 16, v212
	v_and_b32_e32 v255, 0xffff0000, v212
	v_mul_f32_e32 v12, v12, v254
	v_mul_f32_e32 v13, v13, v255
	v_lshlrev_b32_e32 v254, 16, v216
	v_and_b32_e32 v255, 0xffff0000, v216
	v_mul_f32_e32 v12, v12, v254
	v_mul_f32_e32 v13, v13, v255
	v_cvt_pk_bf16_f32 v216, v12, v13
	v_lshlrev_b32_e32 v254, 16, v213
	v_and_b32_e32 v255, 0xffff0000, v213
	v_mul_f32_e32 v14, v14, v254
	v_mul_f32_e32 v15, v15, v255
	v_lshlrev_b32_e32 v254, 16, v217
	v_and_b32_e32 v255, 0xffff0000, v217
	v_mul_f32_e32 v14, v14, v254
	v_mul_f32_e32 v15, v15, v255
	v_cvt_pk_bf16_f32 v217, v14, v15
	v_lshlrev_b32_e32 v254, 16, v214
	v_and_b32_e32 v255, 0xffff0000, v214
	v_mul_f32_e32 v8, v8, v254
	v_mul_f32_e32 v9, v9, v255
	v_lshlrev_b32_e32 v254, 16, v218
	v_and_b32_e32 v255, 0xffff0000, v218
	v_mul_f32_e32 v8, v8, v254
	v_mul_f32_e32 v9, v9, v255
	v_cvt_pk_bf16_f32 v218, v8, v9
	v_lshlrev_b32_e32 v254, 16, v215
	v_and_b32_e32 v255, 0xffff0000, v215
	v_mul_f32_e32 v10, v10, v254
	v_mul_f32_e32 v11, v11, v255
	v_lshlrev_b32_e32 v254, 16, v219
	v_and_b32_e32 v255, 0xffff0000, v219
	v_mul_f32_e32 v10, v10, v254
	v_mul_f32_e32 v11, v11, v255
	v_cvt_pk_bf16_f32 v219, v10, v11
	s_mov_b64 s[100:101], 0x50000
	v_lshl_add_u64 v[190:191], v[248:249], 0, s[100:101]
	global_store_dwordx4 v[190:191], v[216:219], off offset:256
	s_waitcnt vmcnt(7)
	v_pk_add_f32 v[4:5], v[4:5], v[236:237]
	v_pk_add_f32 v[6:7], v[6:7], v[238:239]
	v_pk_add_f32 v[0:1], v[0:1], v[242:243]
	v_pk_add_f32 v[2:3], v[2:3], v[244:245]
	v_mul_f32_e32 v4, 0xbfb8aa3b, v4
	v_mul_f32_e32 v5, 0xbfb8aa3b, v5
	v_mul_f32_e32 v6, 0xbfb8aa3b, v6
	v_mul_f32_e32 v7, 0xbfb8aa3b, v7
	v_mul_f32_e32 v0, 0xbfb8aa3b, v0
	v_mul_f32_e32 v1, 0xbfb8aa3b, v1
	v_mul_f32_e32 v2, 0xbfb8aa3b, v2
	v_mul_f32_e32 v3, 0xbfb8aa3b, v3
	v_exp_f32_e32 v4, v4
	v_exp_f32_e32 v5, v5
	v_exp_f32_e32 v6, v6
	v_exp_f32_e32 v7, v7
	v_exp_f32_e32 v0, v0
	v_exp_f32_e32 v1, v1
	v_exp_f32_e32 v2, v2
	v_exp_f32_e32 v3, v3
	v_add_f32_e32 v4, 1.0, v4
	v_add_f32_e32 v5, 1.0, v5
	v_add_f32_e32 v6, 1.0, v6
	v_add_f32_e32 v7, 1.0, v7
	v_add_f32_e32 v0, 1.0, v0
	v_add_f32_e32 v1, 1.0, v1
	v_add_f32_e32 v2, 1.0, v2
	v_add_f32_e32 v3, 1.0, v3
	v_rcp_f32_e32 v4, v4
	v_rcp_f32_e32 v5, v5
	v_rcp_f32_e32 v6, v6
	v_rcp_f32_e32 v7, v7
	v_rcp_f32_e32 v0, v0
	v_rcp_f32_e32 v1, v1
	v_rcp_f32_e32 v2, v2
	v_rcp_f32_e32 v3, v3
	v_lshlrev_b32_e32 v254, 16, v220
	v_and_b32_e32 v255, 0xffff0000, v220
	v_mul_f32_e32 v4, v4, v254
	v_mul_f32_e32 v5, v5, v255
	v_lshlrev_b32_e32 v254, 16, v232
	v_and_b32_e32 v255, 0xffff0000, v232
	v_mul_f32_e32 v4, v4, v254
	v_mul_f32_e32 v5, v5, v255
	v_cvt_pk_bf16_f32 v232, v4, v5
	v_lshlrev_b32_e32 v254, 16, v221
	v_and_b32_e32 v255, 0xffff0000, v221
	v_mul_f32_e32 v6, v6, v254
	v_mul_f32_e32 v7, v7, v255
	v_lshlrev_b32_e32 v254, 16, v233
	v_and_b32_e32 v255, 0xffff0000, v233
	v_mul_f32_e32 v6, v6, v254
	v_mul_f32_e32 v7, v7, v255
	v_cvt_pk_bf16_f32 v233, v6, v7
	v_lshlrev_b32_e32 v254, 16, v222
	v_and_b32_e32 v255, 0xffff0000, v222
	v_mul_f32_e32 v0, v0, v254
	v_mul_f32_e32 v1, v1, v255
	v_lshlrev_b32_e32 v254, 16, v234
	v_and_b32_e32 v255, 0xffff0000, v234
	v_mul_f32_e32 v0, v0, v254
	v_mul_f32_e32 v1, v1, v255
	v_cvt_pk_bf16_f32 v234, v0, v1
	v_lshlrev_b32_e32 v254, 16, v223
	v_and_b32_e32 v255, 0xffff0000, v223
	v_mul_f32_e32 v2, v2, v254
	v_mul_f32_e32 v3, v3, v255
	v_lshlrev_b32_e32 v254, 16, v235
	v_and_b32_e32 v255, 0xffff0000, v235
	v_mul_f32_e32 v2, v2, v254
	v_mul_f32_e32 v3, v3, v255
	v_cvt_pk_bf16_f32 v235, v2, v3
	s_mov_b64 s[100:101], 0x58000
	v_lshl_add_u64 v[190:191], v[248:249], 0, s[100:101]
	global_store_dwordx4 v[190:191], v[232:235], off offset:256
	s_and_b64 vcc, exec, s[4:5]
	s_cbranch_vccz .LBB0_658
	s_waitcnt vmcnt(0)
	s_cmpk_gt_u32 s2, 0xff
	s_cbranch_scc1 .LBB0_669
	s_barrier

	.amdhsa_kernel _Z11mega_kernel6Params
		.amdhsa_group_segment_fixed_size 8192
		.amdhsa_private_segment_fixed_size 0
		.amdhsa_kernarg_size 608
		.amdhsa_user_sgpr_count 2
		.amdhsa_user_sgpr_dispatch_ptr 0
		.amdhsa_user_sgpr_queue_ptr 0
		.amdhsa_user_sgpr_kernarg_segment_ptr 1
		.amdhsa_user_sgpr_dispatch_id 0
		.amdhsa_user_sgpr_kernarg_preload_length 0
		.amdhsa_user_sgpr_kernarg_preload_offset 0
		.amdhsa_user_sgpr_private_segment_size 0
		.amdhsa_uses_dynamic_stack 0
		.amdhsa_enable_private_segment 0
		.amdhsa_system_sgpr_workgroup_id_x 1
		.amdhsa_system_sgpr_workgroup_id_y 0
		.amdhsa_system_sgpr_workgroup_id_z 0
		.amdhsa_system_sgpr_workgroup_info 0
		.amdhsa_system_vgpr_workitem_id 2
		.amdhsa_next_free_vgpr 256
		.amdhsa_next_free_sgpr 102
		.amdhsa_accum_offset 256
		.amdhsa_reserve_vcc 1
		.amdhsa_float_round_mode_32 0
		.amdhsa_float_round_mode_16_64 0
		.amdhsa_float_denorm_mode_32 3
		.amdhsa_float_denorm_mode_16_64 3
		.amdhsa_dx10_clamp 1
		.amdhsa_ieee_mode 1
		.amdhsa_fp16_overflow 0
		.amdhsa_tg_split 0
		.amdhsa_exception_fp_ieee_invalid_op 0
		.amdhsa_exception_fp_denorm_src 0
		.amdhsa_exception_fp_ieee_div_zero 0
		.amdhsa_exception_fp_ieee_overflow 0
		.amdhsa_exception_fp_ieee_underflow 0
		.amdhsa_exception_fp_ieee_inexact 0
		.amdhsa_exception_int_div_zero 0
	.end_amdhsa_kernel

amdhsa.kernels:
  - .agpr_count:     0
    .args:
      - .offset:         0
        .size:           352
        .value_kind:     by_value
      - .offset:         352
        .size:           4
        .value_kind:     hidden_block_count_x
      - .offset:         356
        .size:           4
        .value_kind:     hidden_block_count_y
      - .offset:         360
        .size:           4
        .value_kind:     hidden_block_count_z
      - .offset:         364
        .size:           2
        .value_kind:     hidden_group_size_x
      - .offset:         366
        .size:           2
        .value_kind:     hidden_group_size_y
      - .offset:         368
        .size:           2
        .value_kind:     hidden_group_size_z
      - .offset:         370
        .size:           2
        .value_kind:     hidden_remainder_x
      - .offset:         372
        .size:           2
        .value_kind:     hidden_remainder_y
      - .offset:         374
        .size:           2
        .value_kind:     hidden_remainder_z
      - .offset:         392
        .size:           8
        .value_kind:     hidden_global_offset_x
      - .offset:         400
        .size:           8
        .value_kind:     hidden_global_offset_y
      - .offset:         408
        .size:           8
        .value_kind:     hidden_global_offset_z
      - .offset:         416
        .size:           2
        .value_kind:     hidden_grid_dims
      - .offset:         440
        .size:           8
        .value_kind:     hidden_multigrid_sync_arg
      - .offset:         472
        .size:           4
        .value_kind:     hidden_dynamic_lds_size
    .group_segment_fixed_size: 8192
    .kernarg_segment_align: 8
    .kernarg_segment_size: 608
    .language:       OpenCL C
    .language_version:
      - 2
      - 0
    .max_flat_workgroup_size: 512
    .name:           _Z11mega_kernel6Params
    .private_segment_fixed_size: 0
    .sgpr_count:     108
    .sgpr_spill_count: 113
    .symbol:         _Z11mega_kernel6Params.kd
    .uniform_work_group_size: 1
    .uses_dynamic_stack: false
    .vgpr_count:     256
    .vgpr_spill_count: 0
    .wavefront_size: 64
